# nt hint also on the read-once loads of norm1, final norm and the out-proj residual reads
# baseline (speedup 1.0000x reference)
; #define PG8_STAGE(bufoff, gbase, voff) do { _Pragma("unroll") for (int _i = 0; _i < 2; ++_i) \
;         __builtin_amdgcn_global_load_lds((const unsigned*)((const char*)(gbase) + (voff)[_i]), (LAS unsigned*)(lds + (bufoff) + ldsw + _i * 8192), 16, 0, 0); } while (0)
; #define PG8_LDA(dst, b, h) do { _Pragma("unroll") for (int m = 0; m < 4; ++m) _Pragma("unroll") for (int k = 0; k < 2; ++k) dst[m][k] = *(const LAS bf16x8*)(lds + PG8_SA(b, h) + aoff + m * 2048 + k * 1024); } while (0)
; #define PG8_LDB(dst, b, h) do { _Pragma("unroll") for (int n = 0; n < 2; ++n) _Pragma("unroll") for (int k = 0; k < 2; ++k) dst[n][k] = *(const LAS bf16x8*)(lds + PG8_SB(b, h) + boff + n * 2048 + k * 1024); } while (0)
; #define PG8_MMA(ai, bj, At, Bt) do { __builtin_amdgcn_s_setprio(1); _Pragma("unroll") for (int m = 0; m < 4; ++m) _Pragma("unroll") for (int n = 0; n < 2; ++n) _Pragma("unroll") for (int k = 0; k < 2; ++k) \
;         acc[ai][bj][m][n] = __builtin_amdgcn_mfma_f32_16x16x32_bf16(Bt[n][k], At[m][k], acc[ai][bj][m][n], 0, 0, 0); __builtin_amdgcn_s_setprio(0); } while (0)
; #define PG8_WAIT_L(n) asm volatile("s_waitcnt lgkmcnt(" #n ")" ::: "memory")
; #define PG8_BAR __builtin_amdgcn_s_barrier()
; #define PG8_SCHED __builtin_amdgcn_sched_barrier(0)
; template <class Epi, class Sched>
; DI void gemm_phase(LAS unsigned char* lds, const Gemm g, const Sched& S, const Epi& E) {
;     ...
;             PG8_LDB(B0, 0, 0); PG8_SCHED; PG8_LDA(At, 0, 0); PG8_STAGE(PG8_SA(1, 1), a1 + hstep, voffA);
;             PG8_WAIT_L(8); PG8_BAR; PG8_WAIT_L(0); PG8_MMA(0, 0, At, B0); PG8_BAR; PG8_SCHED;
;             PG8_LDB(B1, 0, 1); PG8_STAGE(PG8_SB(0, 0), b2, voffB);
;             PG8_BAR; PG8_WAIT_L(0); PG8_MMA(0, 1, At, B1); PG8_BAR;
;             PG8_LDA(At, 0, 1); PG8_STAGE(PG8_SA(0, 0), a2, voffA);
;             PG8_BAR; PG8_WAIT_L(0); PG8_MMA(1, 0, At, B0); PG8_BAR; PG8_SCHED;
.LBB0_1007:
	ds_read_b128 v[140:143], v147
	ds_read_b128 v[154:157], v147 offset:1024
	ds_read_b128 v[158:161], v147 offset:2048
	ds_read_b128 v[164:167], v147 offset:3072
	s_add_u32 s24, s22, 0xfffc0080
	s_addc_u32 s25, s23, -1
	s_cmp_eq_u32 s66, 12
	s_cselect_b32 s27, s47, s25
	s_cselect_b32 s26, s53, s24
	s_cselect_b32 s25, s54, s59
	s_cselect_b32 s24, s55, s58
	s_mov_b32 m0, s36
	v_lshl_add_u64 v[150:151], s[22:23], 0, v[136:137]
	ds_read_b128 v[168:171], v148
	ds_read_b128 v[172:175], v148 offset:1024
	ds_read_b128 v[176:179], v148 offset:2048
	ds_read_b128 v[180:183], v148 offset:3072
	ds_read_b128 v[184:187], v148 offset:4096
	ds_read_b128 v[188:191], v148 offset:5120
	ds_read_b128 v[192:195], v148 offset:6144
	ds_read_b128 v[198:201], v148 offset:7168
	global_load_lds_dwordx4 v[150:151], off
	v_lshl_add_u64 v[150:151], s[22:23], 0, v[138:139]
	s_mov_b32 m0, s37
	s_nop 0
	global_load_lds_dwordx4 v[150:151], off
	s_waitcnt lgkmcnt(8)
	s_barrier
	s_waitcnt lgkmcnt(0)
	s_setprio 1
	s_waitcnt lgkmcnt(0)
	v_mfma_f32_16x16x32_bf16 v[126:129], v[140:143], v[168:171], v[126:129]
	v_mfma_f32_16x16x32_bf16 v[122:125], v[158:161], v[168:171], v[122:125]
	v_mfma_f32_16x16x32_bf16 v[114:117], v[140:143], v[176:179], v[114:117]
	v_mfma_f32_16x16x32_bf16 v[106:109], v[158:161], v[176:179], v[106:109]
	v_mfma_f32_16x16x32_bf16 v[98:101], v[140:143], v[184:187], v[98:101]
	v_mfma_f32_16x16x32_bf16 v[90:93], v[158:161], v[184:187], v[90:93]
	v_mfma_f32_16x16x32_bf16 v[82:85], v[140:143], v[192:195], v[82:85]
	v_mfma_f32_16x16x32_bf16 v[74:77], v[158:161], v[192:195], v[74:77]
	v_mfma_f32_16x16x32_bf16 v[126:129], v[154:157], v[172:175], v[126:129]
	v_mfma_f32_16x16x32_bf16 v[122:125], v[164:167], v[172:175], v[122:125]
	v_mfma_f32_16x16x32_bf16 v[114:117], v[154:157], v[180:183], v[114:117]
	v_mfma_f32_16x16x32_bf16 v[106:109], v[164:167], v[180:183], v[106:109]
	v_mfma_f32_16x16x32_bf16 v[98:101], v[154:157], v[188:191], v[98:101]
	v_mfma_f32_16x16x32_bf16 v[90:93], v[164:167], v[188:191], v[90:93]
	v_mfma_f32_16x16x32_bf16 v[82:85], v[154:157], v[198:201], v[82:85]
	v_mfma_f32_16x16x32_bf16 v[74:77], v[164:167], v[198:201], v[74:77]
	s_setprio 0
	s_barrier
	s_mov_b32 m0, s38
	v_lshl_add_u64 v[150:151], s[24:25], 0, v[132:133]
	ds_read_b128 v[202:205], v149
	ds_read_b128 v[206:209], v149 offset:1024
	ds_read_b128 v[210:213], v149 offset:2048
	ds_read_b128 v[214:217], v149 offset:3072
	global_load_lds_dwordx4 v[150:151], off
	v_lshl_add_u64 v[218:219], s[24:25], 0, v[130:131]
	s_mov_b32 m0, s39
	s_nop 0
	global_load_lds_dwordx4 v[218:219], off
	s_barrier
	s_waitcnt lgkmcnt(0)
	s_setprio 1
	s_waitcnt lgkmcnt(0)
	v_mfma_f32_16x16x32_bf16 v[118:121], v[202:205], v[168:171], v[118:121]
	v_mfma_f32_16x16x32_bf16 v[110:113], v[210:213], v[168:171], v[110:113]
	v_mfma_f32_16x16x32_bf16 v[102:105], v[202:205], v[176:179], v[102:105]
	v_mfma_f32_16x16x32_bf16 v[94:97], v[210:213], v[176:179], v[94:97]
	v_mfma_f32_16x16x32_bf16 v[86:89], v[202:205], v[184:187], v[86:89]
	v_mfma_f32_16x16x32_bf16 v[78:81], v[210:213], v[184:187], v[78:81]
	v_mfma_f32_16x16x32_bf16 v[70:73], v[202:205], v[192:195], v[70:73]
	v_mfma_f32_16x16x32_bf16 v[66:69], v[210:213], v[192:195], v[66:69]
	v_mfma_f32_16x16x32_bf16 v[118:121], v[206:209], v[172:175], v[118:121]
	v_mfma_f32_16x16x32_bf16 v[110:113], v[214:217], v[172:175], v[110:113]
	v_mfma_f32_16x16x32_bf16 v[102:105], v[206:209], v[180:183], v[102:105]
	v_mfma_f32_16x16x32_bf16 v[94:97], v[214:217], v[180:183], v[94:97]
	v_mfma_f32_16x16x32_bf16 v[86:89], v[206:209], v[188:191], v[86:89]
	v_mfma_f32_16x16x32_bf16 v[78:81], v[214:217], v[188:191], v[78:81]
	v_mfma_f32_16x16x32_bf16 v[70:73], v[206:209], v[198:201], v[70:73]
	v_mfma_f32_16x16x32_bf16 v[66:69], v[214:217], v[198:201], v[66:69]
	s_setprio 0
	s_mov_b32 m0, s13
	v_lshl_add_u64 v[220:221], s[26:27], 0, v[132:133]
	s_barrier
	ds_read_b128 v[168:171], v148 offset:16384
	ds_read_b128 v[172:175], v148 offset:17408
	ds_read_b128 v[176:179], v148 offset:18432
	ds_read_b128 v[180:183], v148 offset:19456
	ds_read_b128 v[184:187], v148 offset:20480
	ds_read_b128 v[188:191], v148 offset:21504
	ds_read_b128 v[192:195], v148 offset:22528
	ds_read_b128 v[198:201], v148 offset:23552
	global_load_lds_dwordx4 v[220:221], off
	v_lshl_add_u64 v[222:223], s[26:27], 0, v[130:131]
	s_mov_b32 m0, s28
	s_nop 0
	global_load_lds_dwordx4 v[222:223], off
	s_barrier
	s_waitcnt lgkmcnt(0)
	s_setprio 1
	s_waitcnt lgkmcnt(0)
	v_mfma_f32_16x16x32_bf16 v[62:65], v[140:143], v[168:171], v[62:65]
	v_mfma_f32_16x16x32_bf16 v[58:61], v[158:161], v[168:171], v[58:61]
	v_mfma_f32_16x16x32_bf16 v[50:53], v[140:143], v[176:179], v[50:53]
	v_mfma_f32_16x16x32_bf16 v[42:45], v[158:161], v[176:179], v[42:45]
	v_mfma_f32_16x16x32_bf16 v[34:37], v[140:143], v[184:187], v[34:37]
	v_mfma_f32_16x16x32_bf16 v[26:29], v[158:161], v[184:187], v[26:29]
	v_mfma_f32_16x16x32_bf16 v[18:21], v[140:143], v[192:195], v[18:21]
	v_mfma_f32_16x16x32_bf16 v[10:13], v[158:161], v[192:195], v[10:13]
	v_mfma_f32_16x16x32_bf16 v[62:65], v[154:157], v[172:175], v[62:65]
	v_mfma_f32_16x16x32_bf16 v[58:61], v[164:167], v[172:175], v[58:61]
	v_mfma_f32_16x16x32_bf16 v[50:53], v[154:157], v[180:183], v[50:53]
	v_mfma_f32_16x16x32_bf16 v[42:45], v[164:167], v[180:183], v[42:45]
	v_mfma_f32_16x16x32_bf16 v[34:37], v[154:157], v[188:191], v[34:37]
	v_mfma_f32_16x16x32_bf16 v[26:29], v[164:167], v[188:191], v[26:29]
	v_mfma_f32_16x16x32_bf16 v[18:21], v[154:157], v[198:201], v[18:21]
	v_mfma_f32_16x16x32_bf16 v[10:13], v[164:167], v[198:201], v[10:13]
	s_setprio 0
	s_barrier
; #define PG8_STAGE(bufoff, gbase, voff) do { _Pragma("unroll") for (int _i = 0; _i < 2; ++_i) \
;         __builtin_amdgcn_global_load_lds((const unsigned*)((const char*)(gbase) + (voff)[_i]), (LAS unsigned*)(lds + (bufoff) + ldsw + _i * 8192), 16, 0, 0); } while (0)
; #define PG8_LDA(dst, b, h) do { _Pragma("unroll") for (int m = 0; m < 4; ++m) _Pragma("unroll") for (int k = 0; k < 2; ++k) dst[m][k] = *(const LAS bf16x8*)(lds + PG8_SA(b, h) + aoff + m * 2048 + k * 1024); } while (0)
; #define PG8_LDB(dst, b, h) do { _Pragma("unroll") for (int n = 0; n < 2; ++n) _Pragma("unroll") for (int k = 0; k < 2; ++k) dst[n][k] = *(const LAS bf16x8*)(lds + PG8_SB(b, h) + boff + n * 2048 + k * 1024); } while (0)
; #define PG8_MMA(ai, bj, At, Bt) do { __builtin_amdgcn_s_setprio(1); _Pragma("unroll") for (int m = 0; m < 4; ++m) _Pragma("unroll") for (int n = 0; n < 2; ++n) _Pragma("unroll") for (int k = 0; k < 2; ++k) \
;         acc[ai][bj][m][n] = __builtin_amdgcn_mfma_f32_16x16x32_bf16(Bt[n][k], At[m][k], acc[ai][bj][m][n], 0, 0, 0); __builtin_amdgcn_s_setprio(0); } while (0)
; #define PG8_WAIT_V(n) asm volatile("s_waitcnt vmcnt(" #n ")" ::: "memory")
; #define PG8_WAIT_L(n) asm volatile("s_waitcnt lgkmcnt(" #n ")" ::: "memory")
; #define PG8_BAR __builtin_amdgcn_s_barrier()
; #define PG8_SCHED __builtin_amdgcn_sched_barrier(0)
; template <class Epi, class Sched>
; DI void gemm_phase(LAS unsigned char* lds, const Gemm g, const Sched& S, const Epi& E) {
;     ...
;             PG8_STAGE(PG8_SB(0, 1), b2 + hstep, voffB);
;             PG8_WAIT_V(6); PG8_BAR; PG8_MMA(1, 1, At, B1); PG8_BAR;
;             PG8_LDB(B0, 1, 0); PG8_SCHED; PG8_LDA(At, 1, 0); PG8_STAGE(PG8_SA(0, 1), a2 + hstep, voffA);
;             PG8_WAIT_L(8); PG8_BAR; PG8_WAIT_L(0); PG8_MMA(0, 0, At, B0); PG8_BAR; PG8_SCHED;
;             PG8_LDB(B1, 1, 1); PG8_STAGE(PG8_SB(1, 0), b3, voffB);
;             PG8_BAR; PG8_WAIT_L(0); PG8_MMA(0, 1, At, B1); PG8_BAR;
	s_add_u32 s72, s24, 0x40000
	s_addc_u32 s73, s25, 0
	s_add_i32 s67, s35, s12
	v_lshl_add_u64 v[140:141], s[72:73], 0, v[132:133]
	s_mov_b32 m0, s67
	s_nop 0
	global_load_lds_dwordx4 v[140:141], off
	v_lshl_add_u64 v[140:141], s[72:73], 0, v[130:131]
	s_add_i32 m0, s67, 0x2000
	s_nop 0
	global_load_lds_dwordx4 v[140:141], off
	s_waitcnt vmcnt(6)
	s_barrier
	s_setprio 1
	v_mfma_f32_16x16x32_bf16 v[54:57], v[202:205], v[168:171], v[54:57]
	v_mfma_f32_16x16x32_bf16 v[46:49], v[210:213], v[168:171], v[46:49]
	v_mfma_f32_16x16x32_bf16 v[38:41], v[202:205], v[176:179], v[38:41]
	v_mfma_f32_16x16x32_bf16 v[30:33], v[210:213], v[176:179], v[30:33]
	v_mfma_f32_16x16x32_bf16 v[22:25], v[202:205], v[184:187], v[22:25]
	v_mfma_f32_16x16x32_bf16 v[14:17], v[210:213], v[184:187], v[14:17]
	v_mfma_f32_16x16x32_bf16 v[6:9], v[202:205], v[192:195], v[6:9]
	v_mfma_f32_16x16x32_bf16 v[2:5], v[210:213], v[192:195], v[2:5]
	v_mfma_f32_16x16x32_bf16 v[54:57], v[206:209], v[172:175], v[54:57]
	v_mfma_f32_16x16x32_bf16 v[46:49], v[214:217], v[172:175], v[46:49]
	v_mfma_f32_16x16x32_bf16 v[38:41], v[206:209], v[180:183], v[38:41]
	v_mfma_f32_16x16x32_bf16 v[30:33], v[214:217], v[180:183], v[30:33]
	v_mfma_f32_16x16x32_bf16 v[22:25], v[206:209], v[188:191], v[22:25]
	v_mfma_f32_16x16x32_bf16 v[14:17], v[214:217], v[188:191], v[14:17]
	v_mfma_f32_16x16x32_bf16 v[6:9], v[206:209], v[198:201], v[6:9]
	v_mfma_f32_16x16x32_bf16 v[2:5], v[214:217], v[198:201], v[2:5]
	s_setprio 0
	s_add_i32 s67, 0, 0x18000
	v_add_u32_e32 v134, s67, v145
	s_barrier
	ds_read_b128 v[140:143], v134
	ds_read_b128 v[154:157], v134 offset:1024
	ds_read_b128 v[158:161], v134 offset:2048
	ds_read_b128 v[164:167], v134 offset:3072
	s_add_u32 s26, s26, 0x40000
	s_addc_u32 s27, s27, 0
	s_mov_b32 m0, s29
	v_lshl_add_u64 v[202:203], s[26:27], 0, v[132:133]
	ds_read_b128 v[168:171], v148 offset:32768
	ds_read_b128 v[172:175], v148 offset:33792
	ds_read_b128 v[176:179], v148 offset:34816
	ds_read_b128 v[180:183], v148 offset:35840
	ds_read_b128 v[184:187], v148 offset:36864
	ds_read_b128 v[188:191], v148 offset:37888
	ds_read_b128 v[192:195], v148 offset:38912
	ds_read_b128 v[198:201], v148 offset:39936
	global_load_lds_dwordx4 v[202:203], off
	v_lshl_add_u64 v[202:203], s[26:27], 0, v[130:131]
	s_mov_b32 m0, s30
	s_nop 0
	global_load_lds_dwordx4 v[202:203], off
	s_waitcnt lgkmcnt(8)
	s_barrier
	s_waitcnt lgkmcnt(0)
	s_setprio 1
	s_waitcnt lgkmcnt(0)
	v_mfma_f32_16x16x32_bf16 v[126:129], v[140:143], v[168:171], v[126:129]
	v_mfma_f32_16x16x32_bf16 v[122:125], v[158:161], v[168:171], v[122:125]
	v_mfma_f32_16x16x32_bf16 v[114:117], v[140:143], v[176:179], v[114:117]
	v_mfma_f32_16x16x32_bf16 v[106:109], v[158:161], v[176:179], v[106:109]
	v_mfma_f32_16x16x32_bf16 v[98:101], v[140:143], v[184:187], v[98:101]
	v_mfma_f32_16x16x32_bf16 v[90:93], v[158:161], v[184:187], v[90:93]
	v_mfma_f32_16x16x32_bf16 v[82:85], v[140:143], v[192:195], v[82:85]
	v_mfma_f32_16x16x32_bf16 v[74:77], v[158:161], v[192:195], v[74:77]
	v_mfma_f32_16x16x32_bf16 v[126:129], v[154:157], v[172:175], v[126:129]
	v_mfma_f32_16x16x32_bf16 v[122:125], v[164:167], v[172:175], v[122:125]
	v_mfma_f32_16x16x32_bf16 v[114:117], v[154:157], v[180:183], v[114:117]
	v_mfma_f32_16x16x32_bf16 v[106:109], v[164:167], v[180:183], v[106:109]
	v_mfma_f32_16x16x32_bf16 v[98:101], v[154:157], v[188:191], v[98:101]
	v_mfma_f32_16x16x32_bf16 v[90:93], v[164:167], v[188:191], v[90:93]
	v_mfma_f32_16x16x32_bf16 v[82:85], v[154:157], v[198:201], v[82:85]
	v_mfma_f32_16x16x32_bf16 v[74:77], v[164:167], v[198:201], v[74:77]
	s_setprio 0
	s_barrier
	s_add_i32 s26, 0, 0x1c000
	s_add_i32 s27, s67, s12
	v_add_u32_e32 v134, s26, v145
	v_lshl_add_u64 v[150:151], v[150:151], 0, s[10:11]
	s_mov_b32 m0, s27
	ds_read_b128 v[202:205], v134
	ds_read_b128 v[206:209], v134 offset:1024
	ds_read_b128 v[210:213], v134 offset:2048
	ds_read_b128 v[214:217], v134 offset:3072
	global_load_lds_dwordx4 v[150:151], off
	v_lshl_add_u64 v[150:151], v[218:219], 0, s[10:11]
	s_add_i32 m0, s27, 0x2000
	s_nop 0
	global_load_lds_dwordx4 v[150:151], off
	s_barrier
	s_waitcnt lgkmcnt(0)
	s_setprio 1
	s_waitcnt lgkmcnt(0)
	v_mfma_f32_16x16x32_bf16 v[118:121], v[202:205], v[168:171], v[118:121]
	v_mfma_f32_16x16x32_bf16 v[110:113], v[210:213], v[168:171], v[110:113]
	v_mfma_f32_16x16x32_bf16 v[102:105], v[202:205], v[176:179], v[102:105]
	v_mfma_f32_16x16x32_bf16 v[94:97], v[210:213], v[176:179], v[94:97]
	v_mfma_f32_16x16x32_bf16 v[86:89], v[202:205], v[184:187], v[86:89]
	v_mfma_f32_16x16x32_bf16 v[78:81], v[210:213], v[184:187], v[78:81]
	v_mfma_f32_16x16x32_bf16 v[70:73], v[202:205], v[192:195], v[70:73]
	v_mfma_f32_16x16x32_bf16 v[66:69], v[210:213], v[192:195], v[66:69]
	v_mfma_f32_16x16x32_bf16 v[118:121], v[206:209], v[172:175], v[118:121]
	v_mfma_f32_16x16x32_bf16 v[110:113], v[214:217], v[172:175], v[110:113]
	v_mfma_f32_16x16x32_bf16 v[102:105], v[206:209], v[180:183], v[102:105]
	v_mfma_f32_16x16x32_bf16 v[94:97], v[214:217], v[180:183], v[94:97]
	v_mfma_f32_16x16x32_bf16 v[86:89], v[206:209], v[188:191], v[86:89]
	v_mfma_f32_16x16x32_bf16 v[78:81], v[214:217], v[188:191], v[78:81]
	v_mfma_f32_16x16x32_bf16 v[70:73], v[206:209], v[198:201], v[70:73]
	v_mfma_f32_16x16x32_bf16 v[66:69], v[214:217], v[198:201], v[66:69]
	s_setprio 0
	s_mov_b32 m0, s33
	v_lshl_add_u64 v[150:151], v[220:221], 0, s[10:11]
	s_barrier
	ds_read_b128 v[168:171], v148 offset:49152
	ds_read_b128 v[172:175], v148 offset:50176
	ds_read_b128 v[176:179], v148 offset:51200
	ds_read_b128 v[180:183], v148 offset:52224
	ds_read_b128 v[184:187], v148 offset:53248
	ds_read_b128 v[188:191], v148 offset:54272
	ds_read_b128 v[192:195], v148 offset:55296
	ds_read_b128 v[198:201], v148 offset:56320
	global_load_lds_dwordx4 v[150:151], off
	v_lshl_add_u64 v[150:151], v[222:223], 0, s[10:11]
	s_mov_b32 m0, s34
	s_nop 0
	global_load_lds_dwordx4 v[150:151], off
	s_barrier
; DI unsigned pk_bf16(float a, float b) { f32x2 v = {a, b}; bf2_t r = __builtin_convertvector(v, bf2_t); return __builtin_bit_cast(unsigned, r); }
; DI float bflo(unsigned u) { return __uint_as_float(u << 16); }
; DI float bfhi(unsigned u) { return __uint_as_float(u & 0xffff0000u); }
; #define PG8_STAGE(bufoff, gbase, voff) do { _Pragma("unroll") for (int _i = 0; _i < 2; ++_i) \
;         __builtin_amdgcn_global_load_lds((const unsigned*)((const char*)(gbase) + (voff)[_i]), (LAS unsigned*)(lds + (bufoff) + ldsw + _i * 8192), 16, 0, 0); } while (0)
; #define PG8_LDA(dst, b, h) do { _Pragma("unroll") for (int m = 0; m < 4; ++m) _Pragma("unroll") for (int k = 0; k < 2; ++k) dst[m][k] = *(const LAS bf16x8*)(lds + PG8_SA(b, h) + aoff + m * 2048 + k * 1024); } while (0)
; #define PG8_WAIT_V(n) asm volatile("s_waitcnt vmcnt(" #n ")" ::: "memory")
; #define PG8_WAIT_L(n) asm volatile("s_waitcnt lgkmcnt(" #n ")" ::: "memory")
; #define PG8_BAR __builtin_amdgcn_s_barrier()
;     DI void operator()(const f32x4 (&acc)[2][2][4][2], const Unit& u, int wr, int wc, int fr, int fq) const {
;         const int row0 = u.pm * BM + wr * 64 + fr, col0 = u.pn * BM + wc * 32 + 4 * fq;
; #pragma unroll
;         for (int ai = 0; ai < 2; ++ai)
; #pragma unroll
;             for (int m = 0; m < 4; ++m) { const size_t o = (size_t)(row0 + ai * HALF + m * 16) * 1024 + col0;
; #pragma unroll
;                 for (int bj = 0; bj < 2; ++bj)
; #pragma unroll
;                     for (int n = 0; n < 2; ++n) { const size_t oo = o + bj * HALF + n * 16; f32x4 rv;
;                         if (RES_BF16) { const u32x2 t = *(const u32x2*)((const bf16_t*)res + oo); rv = (f32x4){bflo(t.x), bfhi(t.x), bflo(t.y), bfhi(t.y)}; }
;                         else rv = *(const f32x4*)((const float*)res + oo);
;                         const f32x4 v = acc[ai][bj][m][n] + rv; u32x2 w; w.x = pk_bf16(v.x, v.y); w.y = pk_bf16(v.z, v.w);
;                         *(u32x2*)(O + oo) = w; } }
; template <class Epi, class Sched>
; DI void gemm_phase(LAS unsigned char* lds, const Gemm g, const Sched& S, const Epi& E) {
;     ...
;             PG8_LDA(At, 1, 1); PG8_STAGE(PG8_SA(1, 0), a3, voffA);
;             PG8_BAR; PG8_WAIT_L(0); PG8_MMA(1, 0, At, B0); PG8_BAR; PG8_SCHED;
;             PG8_STAGE(PG8_SB(1, 1), b3 + hstep, voffB);
;             PG8_WAIT_V(6); PG8_BAR; PG8_MMA(1, 1, At, B1); PG8_BAR;
	s_waitcnt lgkmcnt(0)
	s_setprio 1
	s_waitcnt lgkmcnt(0)
	v_mfma_f32_16x16x32_bf16 v[62:65], v[140:143], v[168:171], v[62:65]
	v_mfma_f32_16x16x32_bf16 v[58:61], v[158:161], v[168:171], v[58:61]
	v_mfma_f32_16x16x32_bf16 v[50:53], v[140:143], v[176:179], v[50:53]
	v_mfma_f32_16x16x32_bf16 v[42:45], v[158:161], v[176:179], v[42:45]
	v_mfma_f32_16x16x32_bf16 v[34:37], v[140:143], v[184:187], v[34:37]
	v_mfma_f32_16x16x32_bf16 v[26:29], v[158:161], v[184:187], v[26:29]
	v_mfma_f32_16x16x32_bf16 v[18:21], v[140:143], v[192:195], v[18:21]
	v_mfma_f32_16x16x32_bf16 v[10:13], v[158:161], v[192:195], v[10:13]
	v_mfma_f32_16x16x32_bf16 v[62:65], v[154:157], v[172:175], v[62:65]
	v_mfma_f32_16x16x32_bf16 v[58:61], v[164:167], v[172:175], v[58:61]
	v_mfma_f32_16x16x32_bf16 v[50:53], v[154:157], v[180:183], v[50:53]
	v_mfma_f32_16x16x32_bf16 v[42:45], v[164:167], v[180:183], v[42:45]
	v_mfma_f32_16x16x32_bf16 v[34:37], v[154:157], v[188:191], v[34:37]
	v_mfma_f32_16x16x32_bf16 v[26:29], v[164:167], v[188:191], v[26:29]
	v_mfma_f32_16x16x32_bf16 v[18:21], v[154:157], v[198:201], v[18:21]
	v_mfma_f32_16x16x32_bf16 v[10:13], v[164:167], v[198:201], v[10:13]
	s_setprio 0
	s_barrier
	s_add_u32 s24, s24, 0x40080
	s_addc_u32 s25, s25, 0
	s_add_i32 s26, s26, s12
	v_lshl_add_u64 v[140:141], s[24:25], 0, v[132:133]
	s_mov_b32 m0, s26
	s_nop 0
	global_load_lds_dwordx4 v[140:141], off
	v_lshl_add_u64 v[140:141], s[24:25], 0, v[130:131]
	s_add_i32 m0, s26, 0x2000
	s_nop 0
	global_load_lds_dwordx4 v[140:141], off
	s_waitcnt vmcnt(6)
	s_barrier
	s_setprio 1
	v_mfma_f32_16x16x32_bf16 v[54:57], v[202:205], v[168:171], v[54:57]
	v_mfma_f32_16x16x32_bf16 v[46:49], v[210:213], v[168:171], v[46:49]
	v_mfma_f32_16x16x32_bf16 v[38:41], v[202:205], v[176:179], v[38:41]
	v_mfma_f32_16x16x32_bf16 v[30:33], v[210:213], v[176:179], v[30:33]
	v_mfma_f32_16x16x32_bf16 v[22:25], v[202:205], v[184:187], v[22:25]
	v_mfma_f32_16x16x32_bf16 v[14:17], v[210:213], v[184:187], v[14:17]
	v_mfma_f32_16x16x32_bf16 v[6:9], v[202:205], v[192:195], v[6:9]
	v_mfma_f32_16x16x32_bf16 v[2:5], v[210:213], v[192:195], v[2:5]
	v_mfma_f32_16x16x32_bf16 v[54:57], v[206:209], v[172:175], v[54:57]
	v_mfma_f32_16x16x32_bf16 v[46:49], v[214:217], v[172:175], v[46:49]
	v_mfma_f32_16x16x32_bf16 v[38:41], v[206:209], v[180:183], v[38:41]
	v_mfma_f32_16x16x32_bf16 v[30:33], v[214:217], v[180:183], v[30:33]
	v_mfma_f32_16x16x32_bf16 v[22:25], v[206:209], v[188:191], v[22:25]
	v_mfma_f32_16x16x32_bf16 v[14:17], v[214:217], v[188:191], v[14:17]
	v_mfma_f32_16x16x32_bf16 v[6:9], v[206:209], v[198:201], v[6:9]
	v_mfma_f32_16x16x32_bf16 v[2:5], v[214:217], v[198:201], v[2:5]
	s_setprio 0
	s_add_i32 s66, s66, 2
	s_add_u32 s22, s22, 0x100
	s_addc_u32 s23, s23, 0
	s_add_u32 s58, s58, 0x100
	s_addc_u32 s59, s59, 0
	s_cmp_gt_u32 s66, 13
	s_barrier
	s_cbranch_scc0 .LBB0_1007
	v_lshl_add_u32 v224, s43, 8, v144
	v_lshl_or_b32 v243, s42, 8, v146
	v_lshl_or_b32 v224, v224, 10, v243
	v_lshlrev_b32_e32 v225, 2, v224
	v_lshlrev_b32_e32 v233, 1, v224
	v_add_u32_e32 v234, 0x4000, v224
	v_lshlrev_b32_e32 v226, 2, v234
	v_lshlrev_b32_e32 v234, 1, v234
	v_add_u32_e32 v235, 0x8000, v224
	v_lshlrev_b32_e32 v227, 2, v235
	v_lshlrev_b32_e32 v235, 1, v235
	v_add_u32_e32 v236, 0xc000, v224
	v_lshlrev_b32_e32 v228, 2, v236
	v_lshlrev_b32_e32 v236, 1, v236
	v_add_u32_e32 v237, 0x20000, v224
	v_lshlrev_b32_e32 v229, 2, v237
	v_lshlrev_b32_e32 v237, 1, v237
	v_add_u32_e32 v240, 0x24000, v224
	v_lshlrev_b32_e32 v230, 2, v240
	v_lshlrev_b32_e32 v240, 1, v240
	v_add_u32_e32 v241, 0x28000, v224
	v_lshlrev_b32_e32 v231, 2, v241
	v_lshlrev_b32_e32 v241, 1, v241
	v_add_u32_e32 v242, 0x2c000, v224
	v_lshlrev_b32_e32 v232, 2, v242
	v_lshlrev_b32_e32 v242, 1, v242
	v_and_b32_e32 v248, 63, v1
	v_lshrrev_b32_e32 v249, 3, v248
	v_and_b32_e32 v250, 3, v248
	v_lshl_or_b32 v250, v250, 4, v249
	v_lshlrev_b32_e32 v244, 2, v250
	v_add_u32_e32 v245, 32, v244
	v_and_b32_e32 v250, 0xffffffc0, v144
	v_add_u32_e32 v250, v250, v249
	v_lshl_add_u32 v250, s43, 8, v250
	v_mul_u32_u24_e32 v250, 0x800, v250
	v_and_b32_e32 v247, 0xffffffe0, v146
	v_lshl_or_b32 v247, s42, 8, v247
	v_lshlrev_b32_e32 v247, 1, v247
	v_and_b32_e32 v248, 7, v248
	v_lshl_add_u32 v247, v248, 3, v247
	v_add_u32_e32 v246, v250, v247
	s_mov_b32 s98, 0xf0f0f0f0
	s_mov_b32 s99, 0xf0f0f0f0
	global_load_dwordx4 v[140:143], v225, s[60:61] nt
	global_load_dwordx4 v[154:157], v225, s[60:61] offset:64 nt
	global_load_dwordx4 v[158:161], v225, s[60:61] offset:512 nt
	global_load_dwordx4 v[164:167], v225, s[60:61] offset:576 nt
	global_load_dwordx4 v[168:171], v226, s[60:61] nt
	global_load_dwordx4 v[172:175], v226, s[60:61] offset:64 nt
	global_load_dwordx4 v[176:179], v226, s[60:61] offset:512 nt
	global_load_dwordx4 v[180:183], v226, s[60:61] offset:576 nt
	global_load_dwordx4 v[184:187], v227, s[60:61] nt
	global_load_dwordx4 v[188:191], v227, s[60:61] offset:64 nt
	global_load_dwordx4 v[192:195], v227, s[60:61] offset:512 nt
	global_load_dwordx4 v[198:201], v227, s[60:61] offset:576 nt
	global_load_dwordx4 v[202:205], v228, s[60:61] nt
	global_load_dwordx4 v[206:209], v228, s[60:61] offset:64 nt
	global_load_dwordx4 v[210:213], v228, s[60:61] offset:512 nt
	global_load_dwordx4 v[214:217], v228, s[60:61] offset:576 nt
	s_waitcnt vmcnt(12)
; DI unsigned pk_bf16(float a, float b) { f32x2 v = {a, b}; bf2_t r = __builtin_convertvector(v, bf2_t); return __builtin_bit_cast(unsigned, r); }
; DI float bflo(unsigned u) { return __uint_as_float(u << 16); }
; DI float bfhi(unsigned u) { return __uint_as_float(u & 0xffff0000u); }
;     DI void operator()(const f32x4 (&acc)[2][2][4][2], const Unit& u, int wr, int wc, int fr, int fq) const {
;         const int row0 = u.pm * BM + wr * 64 + fr, col0 = u.pn * BM + wc * 32 + 4 * fq;
; #pragma unroll
;         for (int ai = 0; ai < 2; ++ai)
; #pragma unroll
;             for (int m = 0; m < 4; ++m) { const size_t o = (size_t)(row0 + ai * HALF + m * 16) * 1024 + col0;
; #pragma unroll
;                 for (int bj = 0; bj < 2; ++bj)
; #pragma unroll
;                     for (int n = 0; n < 2; ++n) { const size_t oo = o + bj * HALF + n * 16; f32x4 rv;
;                         if (RES_BF16) { const u32x2 t = *(const u32x2*)((const bf16_t*)res + oo); rv = (f32x4){bflo(t.x), bfhi(t.x), bflo(t.y), bfhi(t.y)}; }
;                         else rv = *(const f32x4*)((const float*)res + oo);
;                         const f32x4 v = acc[ai][bj][m][n] + rv; u32x2 w; w.x = pk_bf16(v.x, v.y); w.y = pk_bf16(v.z, v.w);
;                         *(u32x2*)(O + oo) = w; } }
	v_pk_add_f32 v[128:129], v[128:129], v[142:143]
	v_pk_add_f32 v[126:127], v[126:127], v[140:141]
	v_pk_add_f32 v[124:125], v[124:125], v[156:157]
	v_pk_add_f32 v[122:123], v[122:123], v[154:155]
	v_pk_add_f32 v[120:121], v[120:121], v[160:161]
	v_pk_add_f32 v[118:119], v[118:119], v[158:159]
	v_pk_add_f32 v[112:113], v[112:113], v[166:167]
	v_pk_add_f32 v[110:111], v[110:111], v[164:165]
	v_cvt_pk_bf16_f32 v126, v126, v127
	v_cvt_pk_bf16_f32 v127, v128, v129
	v_cvt_pk_bf16_f32 v122, v122, v123
	v_cvt_pk_bf16_f32 v123, v124, v125
	v_cvt_pk_bf16_f32 v118, v118, v119
	v_cvt_pk_bf16_f32 v119, v120, v121
	v_cvt_pk_bf16_f32 v110, v110, v111
	v_cvt_pk_bf16_f32 v111, v112, v113
	ds_bpermute_b32 v140, v244, v126
	ds_bpermute_b32 v141, v244, v127
	ds_bpermute_b32 v142, v244, v122
	ds_bpermute_b32 v143, v244, v123
	ds_bpermute_b32 v154, v245, v126
	ds_bpermute_b32 v155, v245, v127
	ds_bpermute_b32 v156, v245, v122
	ds_bpermute_b32 v157, v245, v123
	s_waitcnt lgkmcnt(0)
	v_cndmask_b32_e64 v140, v140, v142, s[98:99]
	v_cndmask_b32_e64 v141, v141, v143, s[98:99]
	v_mov_b32_e32 v142, v246
	global_store_dwordx2 v142, v[140:141], s[48:49]
	v_cndmask_b32_e64 v154, v154, v156, s[98:99]
	v_cndmask_b32_e64 v155, v155, v157, s[98:99]
	v_add_u32_e32 v156, 0x4000, v246
	global_store_dwordx2 v156, v[154:155], s[48:49]
	ds_bpermute_b32 v140, v244, v118
	ds_bpermute_b32 v141, v244, v119
	ds_bpermute_b32 v142, v244, v110
	ds_bpermute_b32 v143, v244, v111
	ds_bpermute_b32 v154, v245, v118
	ds_bpermute_b32 v155, v245, v119
	ds_bpermute_b32 v156, v245, v110
	ds_bpermute_b32 v157, v245, v111
	s_waitcnt lgkmcnt(0)
	v_cndmask_b32_e64 v140, v140, v142, s[98:99]
	v_cndmask_b32_e64 v141, v141, v143, s[98:99]
	v_mov_b32_e32 v142, v246
	global_store_dwordx2 v142, v[140:141], s[48:49] offset:256
	v_cndmask_b32_e64 v154, v154, v156, s[98:99]
	v_cndmask_b32_e64 v155, v155, v157, s[98:99]
	v_add_u32_e32 v156, 0x4000, v246
	global_store_dwordx2 v156, v[154:155], s[48:49] offset:256
	global_load_dwordx4 v[140:143], v229, s[60:61] nt
	global_load_dwordx4 v[154:157], v229, s[60:61] offset:64 nt
	global_load_dwordx4 v[158:161], v229, s[60:61] offset:512 nt
	global_load_dwordx4 v[164:167], v229, s[60:61] offset:576 nt
	s_waitcnt vmcnt(16)
	v_pk_add_f32 v[116:117], v[116:117], v[170:171]
	v_pk_add_f32 v[114:115], v[114:115], v[168:169]
	v_pk_add_f32 v[108:109], v[108:109], v[174:175]
	v_pk_add_f32 v[106:107], v[106:107], v[172:173]
	v_pk_add_f32 v[104:105], v[104:105], v[178:179]
	v_pk_add_f32 v[102:103], v[102:103], v[176:177]
	v_pk_add_f32 v[96:97], v[96:97], v[182:183]
	v_pk_add_f32 v[94:95], v[94:95], v[180:181]
	v_cvt_pk_bf16_f32 v114, v114, v115
	v_cvt_pk_bf16_f32 v115, v116, v117
	v_cvt_pk_bf16_f32 v106, v106, v107
	v_cvt_pk_bf16_f32 v107, v108, v109
	v_cvt_pk_bf16_f32 v102, v102, v103
	v_cvt_pk_bf16_f32 v103, v104, v105
	v_cvt_pk_bf16_f32 v94, v94, v95
	v_cvt_pk_bf16_f32 v95, v96, v97
	ds_bpermute_b32 v168, v244, v114
	ds_bpermute_b32 v169, v244, v115
	ds_bpermute_b32 v170, v244, v106
	ds_bpermute_b32 v171, v244, v107
	ds_bpermute_b32 v172, v245, v114
	ds_bpermute_b32 v173, v245, v115
	ds_bpermute_b32 v174, v245, v106
	ds_bpermute_b32 v175, v245, v107
	s_waitcnt lgkmcnt(0)
	v_cndmask_b32_e64 v168, v168, v170, s[98:99]
	v_cndmask_b32_e64 v169, v169, v171, s[98:99]
	v_add_u32_e32 v170, 0x8000, v246
	global_store_dwordx2 v170, v[168:169], s[48:49]
	v_cndmask_b32_e64 v172, v172, v174, s[98:99]
	v_cndmask_b32_e64 v173, v173, v175, s[98:99]
	v_add_u32_e32 v174, 0xc000, v246
	global_store_dwordx2 v174, v[172:173], s[48:49]
	ds_bpermute_b32 v168, v244, v102
	ds_bpermute_b32 v169, v244, v103
	ds_bpermute_b32 v170, v244, v94
	ds_bpermute_b32 v171, v244, v95
	ds_bpermute_b32 v172, v245, v102
	ds_bpermute_b32 v173, v245, v103
	ds_bpermute_b32 v174, v245, v94
	ds_bpermute_b32 v175, v245, v95
	s_waitcnt lgkmcnt(0)
	v_cndmask_b32_e64 v168, v168, v170, s[98:99]
	v_cndmask_b32_e64 v169, v169, v171, s[98:99]
	v_add_u32_e32 v170, 0x8000, v246
	global_store_dwordx2 v170, v[168:169], s[48:49] offset:256
	v_cndmask_b32_e64 v172, v172, v174, s[98:99]
	v_cndmask_b32_e64 v173, v173, v175, s[98:99]
	v_add_u32_e32 v174, 0xc000, v246
	global_store_dwordx2 v174, v[172:173], s[48:49] offset:256
	global_load_dwordx4 v[168:171], v230, s[60:61] nt
	global_load_dwordx4 v[172:175], v230, s[60:61] offset:64 nt
	global_load_dwordx4 v[176:179], v230, s[60:61] offset:512 nt
	global_load_dwordx4 v[180:183], v230, s[60:61] offset:576 nt
	s_waitcnt vmcnt(20)
	v_pk_add_f32 v[100:101], v[100:101], v[186:187]
	v_pk_add_f32 v[98:99], v[98:99], v[184:185]
	v_pk_add_f32 v[92:93], v[92:93], v[190:191]
	v_pk_add_f32 v[90:91], v[90:91], v[188:189]
	v_pk_add_f32 v[88:89], v[88:89], v[194:195]
	v_pk_add_f32 v[86:87], v[86:87], v[192:193]
	v_pk_add_f32 v[80:81], v[80:81], v[200:201]
	v_pk_add_f32 v[78:79], v[78:79], v[198:199]
	v_cvt_pk_bf16_f32 v98, v98, v99
	v_cvt_pk_bf16_f32 v99, v100, v101
	v_cvt_pk_bf16_f32 v90, v90, v91
	v_cvt_pk_bf16_f32 v91, v92, v93
	v_cvt_pk_bf16_f32 v86, v86, v87
	v_cvt_pk_bf16_f32 v87, v88, v89
	v_cvt_pk_bf16_f32 v78, v78, v79
	v_cvt_pk_bf16_f32 v79, v80, v81
	ds_bpermute_b32 v184, v244, v98
	ds_bpermute_b32 v185, v244, v99
	ds_bpermute_b32 v186, v244, v90
	ds_bpermute_b32 v187, v244, v91
	ds_bpermute_b32 v188, v245, v98
	ds_bpermute_b32 v189, v245, v99
	ds_bpermute_b32 v190, v245, v90
	ds_bpermute_b32 v191, v245, v91
	s_waitcnt lgkmcnt(0)
; DI unsigned pk_bf16(float a, float b) { f32x2 v = {a, b}; bf2_t r = __builtin_convertvector(v, bf2_t); return __builtin_bit_cast(unsigned, r); }
; DI float bflo(unsigned u) { return __uint_as_float(u << 16); }
; DI float bfhi(unsigned u) { return __uint_as_float(u & 0xffff0000u); }
;     DI void operator()(const f32x4 (&acc)[2][2][4][2], const Unit& u, int wr, int wc, int fr, int fq) const {
;         const int row0 = u.pm * BM + wr * 64 + fr, col0 = u.pn * BM + wc * 32 + 4 * fq;
; #pragma unroll
;         for (int ai = 0; ai < 2; ++ai)
; #pragma unroll
;             for (int m = 0; m < 4; ++m) { const size_t o = (size_t)(row0 + ai * HALF + m * 16) * 1024 + col0;
; #pragma unroll
;                 for (int bj = 0; bj < 2; ++bj)
; #pragma unroll
;                     for (int n = 0; n < 2; ++n) { const size_t oo = o + bj * HALF + n * 16; f32x4 rv;
;                         if (RES_BF16) { const u32x2 t = *(const u32x2*)((const bf16_t*)res + oo); rv = (f32x4){bflo(t.x), bfhi(t.x), bflo(t.y), bfhi(t.y)}; }
;                         else rv = *(const f32x4*)((const float*)res + oo);
;                         const f32x4 v = acc[ai][bj][m][n] + rv; u32x2 w; w.x = pk_bf16(v.x, v.y); w.y = pk_bf16(v.z, v.w);
;                         *(u32x2*)(O + oo) = w; } }
	v_cndmask_b32_e64 v184, v184, v186, s[98:99]
	v_cndmask_b32_e64 v185, v185, v187, s[98:99]
	v_add_u32_e32 v186, 0x10000, v246
	global_store_dwordx2 v186, v[184:185], s[48:49]
	v_cndmask_b32_e64 v188, v188, v190, s[98:99]
	v_cndmask_b32_e64 v189, v189, v191, s[98:99]
	v_add_u32_e32 v190, 0x14000, v246
	global_store_dwordx2 v190, v[188:189], s[48:49]
	ds_bpermute_b32 v184, v244, v86
	ds_bpermute_b32 v185, v244, v87
	ds_bpermute_b32 v186, v244, v78
	ds_bpermute_b32 v187, v244, v79
	ds_bpermute_b32 v188, v245, v86
	ds_bpermute_b32 v189, v245, v87
	ds_bpermute_b32 v190, v245, v78
	ds_bpermute_b32 v191, v245, v79
	s_waitcnt lgkmcnt(0)
	v_cndmask_b32_e64 v184, v184, v186, s[98:99]
	v_cndmask_b32_e64 v185, v185, v187, s[98:99]
	v_add_u32_e32 v186, 0x10000, v246
	global_store_dwordx2 v186, v[184:185], s[48:49] offset:256
	v_cndmask_b32_e64 v188, v188, v190, s[98:99]
	v_cndmask_b32_e64 v189, v189, v191, s[98:99]
	v_add_u32_e32 v190, 0x14000, v246
	global_store_dwordx2 v190, v[188:189], s[48:49] offset:256
	global_load_dwordx4 v[184:187], v231, s[60:61] nt
	global_load_dwordx4 v[188:191], v231, s[60:61] offset:64 nt
	global_load_dwordx4 v[192:195], v231, s[60:61] offset:512 nt
	global_load_dwordx4 v[198:201], v231, s[60:61] offset:576 nt
	s_waitcnt vmcnt(24)
	v_pk_add_f32 v[84:85], v[84:85], v[204:205]
	v_pk_add_f32 v[82:83], v[82:83], v[202:203]
	v_pk_add_f32 v[76:77], v[76:77], v[208:209]
	v_pk_add_f32 v[74:75], v[74:75], v[206:207]
	v_pk_add_f32 v[72:73], v[72:73], v[212:213]
	v_pk_add_f32 v[70:71], v[70:71], v[210:211]
	v_pk_add_f32 v[68:69], v[68:69], v[216:217]
	v_pk_add_f32 v[66:67], v[66:67], v[214:215]
	v_cvt_pk_bf16_f32 v82, v82, v83
	v_cvt_pk_bf16_f32 v83, v84, v85
	v_cvt_pk_bf16_f32 v74, v74, v75
	v_cvt_pk_bf16_f32 v75, v76, v77
	v_cvt_pk_bf16_f32 v70, v70, v71
	v_cvt_pk_bf16_f32 v71, v72, v73
	v_cvt_pk_bf16_f32 v66, v66, v67
	v_cvt_pk_bf16_f32 v67, v68, v69
	ds_bpermute_b32 v202, v244, v82
	ds_bpermute_b32 v203, v244, v83
	ds_bpermute_b32 v204, v244, v74
	ds_bpermute_b32 v205, v244, v75
	ds_bpermute_b32 v206, v245, v82
	ds_bpermute_b32 v207, v245, v83
	ds_bpermute_b32 v208, v245, v74
	ds_bpermute_b32 v209, v245, v75
	s_waitcnt lgkmcnt(0)
	v_cndmask_b32_e64 v202, v202, v204, s[98:99]
	v_cndmask_b32_e64 v203, v203, v205, s[98:99]
	v_add_u32_e32 v204, 0x18000, v246
	global_store_dwordx2 v204, v[202:203], s[48:49]
	v_cndmask_b32_e64 v206, v206, v208, s[98:99]
	v_cndmask_b32_e64 v207, v207, v209, s[98:99]
	v_add_u32_e32 v208, 0x1c000, v246
	global_store_dwordx2 v208, v[206:207], s[48:49]
	ds_bpermute_b32 v202, v244, v70
	ds_bpermute_b32 v203, v244, v71
	ds_bpermute_b32 v204, v244, v66
	ds_bpermute_b32 v205, v244, v67
	ds_bpermute_b32 v206, v245, v70
	ds_bpermute_b32 v207, v245, v71
	ds_bpermute_b32 v208, v245, v66
	ds_bpermute_b32 v209, v245, v67
	s_waitcnt lgkmcnt(0)
	v_cndmask_b32_e64 v202, v202, v204, s[98:99]
	v_cndmask_b32_e64 v203, v203, v205, s[98:99]
	v_add_u32_e32 v204, 0x18000, v246
	global_store_dwordx2 v204, v[202:203], s[48:49] offset:256
	v_cndmask_b32_e64 v206, v206, v208, s[98:99]
	v_cndmask_b32_e64 v207, v207, v209, s[98:99]
	v_add_u32_e32 v208, 0x1c000, v246
	global_store_dwordx2 v208, v[206:207], s[48:49] offset:256
	global_load_dwordx4 v[202:205], v232, s[60:61] nt
	global_load_dwordx4 v[206:209], v232, s[60:61] offset:64 nt
	global_load_dwordx4 v[210:213], v232, s[60:61] offset:512 nt
	global_load_dwordx4 v[214:217], v232, s[60:61] offset:576 nt
	s_waitcnt vmcnt(24)
	v_pk_add_f32 v[64:65], v[64:65], v[142:143]
	v_pk_add_f32 v[62:63], v[62:63], v[140:141]
	v_pk_add_f32 v[60:61], v[60:61], v[156:157]
	v_pk_add_f32 v[58:59], v[58:59], v[154:155]
	v_pk_add_f32 v[56:57], v[56:57], v[160:161]
	v_pk_add_f32 v[54:55], v[54:55], v[158:159]
	v_pk_add_f32 v[48:49], v[48:49], v[166:167]
	v_pk_add_f32 v[46:47], v[46:47], v[164:165]
	v_cvt_pk_bf16_f32 v62, v62, v63
	v_cvt_pk_bf16_f32 v63, v64, v65
	v_cvt_pk_bf16_f32 v58, v58, v59
	v_cvt_pk_bf16_f32 v59, v60, v61
	v_cvt_pk_bf16_f32 v54, v54, v55
	v_cvt_pk_bf16_f32 v55, v56, v57
	v_cvt_pk_bf16_f32 v46, v46, v47
	v_cvt_pk_bf16_f32 v47, v48, v49
	ds_bpermute_b32 v140, v244, v62
	ds_bpermute_b32 v141, v244, v63
	ds_bpermute_b32 v142, v244, v58
	ds_bpermute_b32 v143, v244, v59
	ds_bpermute_b32 v154, v245, v62
	ds_bpermute_b32 v155, v245, v63
	ds_bpermute_b32 v156, v245, v58
	ds_bpermute_b32 v157, v245, v59
	s_waitcnt lgkmcnt(0)
	v_cndmask_b32_e64 v140, v140, v142, s[98:99]
	v_cndmask_b32_e64 v141, v141, v143, s[98:99]
	v_add_u32_e32 v142, 0x40000, v246
	global_store_dwordx2 v142, v[140:141], s[48:49]
	v_cndmask_b32_e64 v154, v154, v156, s[98:99]
	v_cndmask_b32_e64 v155, v155, v157, s[98:99]
	v_add_u32_e32 v156, 0x44000, v246
	global_store_dwordx2 v156, v[154:155], s[48:49]
	ds_bpermute_b32 v140, v244, v54
	ds_bpermute_b32 v141, v244, v55
	ds_bpermute_b32 v142, v244, v46
	ds_bpermute_b32 v143, v244, v47
	ds_bpermute_b32 v154, v245, v54
	ds_bpermute_b32 v155, v245, v55
	ds_bpermute_b32 v156, v245, v46
	ds_bpermute_b32 v157, v245, v47
	s_waitcnt lgkmcnt(0)
	v_cndmask_b32_e64 v140, v140, v142, s[98:99]
	v_cndmask_b32_e64 v141, v141, v143, s[98:99]
	v_add_u32_e32 v142, 0x40000, v246
	global_store_dwordx2 v142, v[140:141], s[48:49] offset:256
	v_cndmask_b32_e64 v154, v154, v156, s[98:99]
	v_cndmask_b32_e64 v155, v155, v157, s[98:99]
	v_add_u32_e32 v156, 0x44000, v246
	global_store_dwordx2 v156, v[154:155], s[48:49] offset:256
	s_waitcnt vmcnt(20)
; DI unsigned pk_bf16(float a, float b) { f32x2 v = {a, b}; bf2_t r = __builtin_convertvector(v, bf2_t); return __builtin_bit_cast(unsigned, r); }
; DI float bflo(unsigned u) { return __uint_as_float(u << 16); }
; DI float bfhi(unsigned u) { return __uint_as_float(u & 0xffff0000u); }
; #define PG8_WAIT_V(n) asm volatile("s_waitcnt vmcnt(" #n ")" ::: "memory")
; #define PG8_BAR __builtin_amdgcn_s_barrier()
;     DI void operator()(const f32x4 (&acc)[2][2][4][2], const Unit& u, int wr, int wc, int fr, int fq) const {
;         const int row0 = u.pm * BM + wr * 64 + fr, col0 = u.pn * BM + wc * 32 + 4 * fq;
; #pragma unroll
;         for (int ai = 0; ai < 2; ++ai)
; #pragma unroll
;             for (int m = 0; m < 4; ++m) { const size_t o = (size_t)(row0 + ai * HALF + m * 16) * 1024 + col0;
; #pragma unroll
;                 for (int bj = 0; bj < 2; ++bj)
; #pragma unroll
;                     for (int n = 0; n < 2; ++n) { const size_t oo = o + bj * HALF + n * 16; f32x4 rv;
;                         if (RES_BF16) { const u32x2 t = *(const u32x2*)((const bf16_t*)res + oo); rv = (f32x4){bflo(t.x), bfhi(t.x), bflo(t.y), bfhi(t.y)}; }
;                         else rv = *(const f32x4*)((const float*)res + oo);
;                         const f32x4 v = acc[ai][bj][m][n] + rv; u32x2 w; w.x = pk_bf16(v.x, v.y); w.y = pk_bf16(v.z, v.w);
;                         *(u32x2*)(O + oo) = w; } }
; template <class Epi, class Sched>
; DI void gemm_phase(LAS unsigned char* lds, const Gemm g, const Sched& S, const Epi& E) {
;     ...
;         E(acc, cur, wr, wc, fr, fq);
;         if (!has_next) break;
; #pragma unroll
;         for (int a = 0; a < 2; ++a)
; #pragma unroll
;             for (int b = 0; b < 2; ++b)
; #pragma unroll
;                 for (int m = 0; m < 4; ++m)
; #pragma unroll
;                     for (int n = 0; n < 2; ++n) acc[a][b][m][n] = (f32x4){0.f, 0.f, 0.f, 0.f};
;         cur = nxt; cA = nA; cB = nB; ++ui;
;     }
;     PG8_WAIT_V(0);
;     if (wr == 0) PG8_BAR;
;     PG8_BAR;
	v_pk_add_f32 v[52:53], v[52:53], v[170:171]
	v_pk_add_f32 v[50:51], v[50:51], v[168:169]
	v_pk_add_f32 v[44:45], v[44:45], v[174:175]
	v_pk_add_f32 v[42:43], v[42:43], v[172:173]
	v_pk_add_f32 v[40:41], v[40:41], v[178:179]
	v_pk_add_f32 v[38:39], v[38:39], v[176:177]
	v_pk_add_f32 v[32:33], v[32:33], v[182:183]
	v_pk_add_f32 v[30:31], v[30:31], v[180:181]
	v_cvt_pk_bf16_f32 v50, v50, v51
	v_cvt_pk_bf16_f32 v51, v52, v53
	v_cvt_pk_bf16_f32 v42, v42, v43
	v_cvt_pk_bf16_f32 v43, v44, v45
	v_cvt_pk_bf16_f32 v38, v38, v39
	v_cvt_pk_bf16_f32 v39, v40, v41
	v_cvt_pk_bf16_f32 v30, v30, v31
	v_cvt_pk_bf16_f32 v31, v32, v33
	ds_bpermute_b32 v168, v244, v50
	ds_bpermute_b32 v169, v244, v51
	ds_bpermute_b32 v170, v244, v42
	ds_bpermute_b32 v171, v244, v43
	ds_bpermute_b32 v172, v245, v50
	ds_bpermute_b32 v173, v245, v51
	ds_bpermute_b32 v174, v245, v42
	ds_bpermute_b32 v175, v245, v43
	s_waitcnt lgkmcnt(0)
	v_cndmask_b32_e64 v168, v168, v170, s[98:99]
	v_cndmask_b32_e64 v169, v169, v171, s[98:99]
	v_add_u32_e32 v170, 0x48000, v246
	global_store_dwordx2 v170, v[168:169], s[48:49]
	v_cndmask_b32_e64 v172, v172, v174, s[98:99]
	v_cndmask_b32_e64 v173, v173, v175, s[98:99]
	v_add_u32_e32 v174, 0x4c000, v246
	global_store_dwordx2 v174, v[172:173], s[48:49]
	ds_bpermute_b32 v168, v244, v38
	ds_bpermute_b32 v169, v244, v39
	ds_bpermute_b32 v170, v244, v30
	ds_bpermute_b32 v171, v244, v31
	ds_bpermute_b32 v172, v245, v38
	ds_bpermute_b32 v173, v245, v39
	ds_bpermute_b32 v174, v245, v30
	ds_bpermute_b32 v175, v245, v31
	s_waitcnt lgkmcnt(0)
	v_cndmask_b32_e64 v168, v168, v170, s[98:99]
	v_cndmask_b32_e64 v169, v169, v171, s[98:99]
	v_add_u32_e32 v170, 0x48000, v246
	global_store_dwordx2 v170, v[168:169], s[48:49] offset:256
	v_cndmask_b32_e64 v172, v172, v174, s[98:99]
	v_cndmask_b32_e64 v173, v173, v175, s[98:99]
	v_add_u32_e32 v174, 0x4c000, v246
	global_store_dwordx2 v174, v[172:173], s[48:49] offset:256
	s_waitcnt vmcnt(16)
	v_pk_add_f32 v[36:37], v[36:37], v[186:187]
	v_pk_add_f32 v[34:35], v[34:35], v[184:185]
	v_pk_add_f32 v[28:29], v[28:29], v[190:191]
	v_pk_add_f32 v[26:27], v[26:27], v[188:189]
	v_pk_add_f32 v[24:25], v[24:25], v[194:195]
	v_pk_add_f32 v[22:23], v[22:23], v[192:193]
	v_pk_add_f32 v[16:17], v[16:17], v[200:201]
	v_pk_add_f32 v[14:15], v[14:15], v[198:199]
	v_cvt_pk_bf16_f32 v34, v34, v35
	v_cvt_pk_bf16_f32 v35, v36, v37
	v_cvt_pk_bf16_f32 v26, v26, v27
	v_cvt_pk_bf16_f32 v27, v28, v29
	v_cvt_pk_bf16_f32 v22, v22, v23
	v_cvt_pk_bf16_f32 v23, v24, v25
	v_cvt_pk_bf16_f32 v14, v14, v15
	v_cvt_pk_bf16_f32 v15, v16, v17
	ds_bpermute_b32 v184, v244, v34
	ds_bpermute_b32 v185, v244, v35
	ds_bpermute_b32 v186, v244, v26
	ds_bpermute_b32 v187, v244, v27
	ds_bpermute_b32 v188, v245, v34
	ds_bpermute_b32 v189, v245, v35
	ds_bpermute_b32 v190, v245, v26
	ds_bpermute_b32 v191, v245, v27
	s_waitcnt lgkmcnt(0)
	v_cndmask_b32_e64 v184, v184, v186, s[98:99]
	v_cndmask_b32_e64 v185, v185, v187, s[98:99]
	v_add_u32_e32 v186, 0x50000, v246
	global_store_dwordx2 v186, v[184:185], s[48:49]
	v_cndmask_b32_e64 v188, v188, v190, s[98:99]
	v_cndmask_b32_e64 v189, v189, v191, s[98:99]
	v_add_u32_e32 v190, 0x54000, v246
	global_store_dwordx2 v190, v[188:189], s[48:49]
	ds_bpermute_b32 v184, v244, v22
	ds_bpermute_b32 v185, v244, v23
	ds_bpermute_b32 v186, v244, v14
	ds_bpermute_b32 v187, v244, v15
	ds_bpermute_b32 v188, v245, v22
	ds_bpermute_b32 v189, v245, v23
	ds_bpermute_b32 v190, v245, v14
	ds_bpermute_b32 v191, v245, v15
	s_waitcnt lgkmcnt(0)
	v_cndmask_b32_e64 v184, v184, v186, s[98:99]
	v_cndmask_b32_e64 v185, v185, v187, s[98:99]
	v_add_u32_e32 v186, 0x50000, v246
	global_store_dwordx2 v186, v[184:185], s[48:49] offset:256
	v_cndmask_b32_e64 v188, v188, v190, s[98:99]
	v_cndmask_b32_e64 v189, v189, v191, s[98:99]
	v_add_u32_e32 v190, 0x54000, v246
	global_store_dwordx2 v190, v[188:189], s[48:49] offset:256
	s_waitcnt vmcnt(12)
	v_pk_add_f32 v[20:21], v[20:21], v[204:205]
	v_pk_add_f32 v[18:19], v[18:19], v[202:203]
	v_pk_add_f32 v[12:13], v[12:13], v[208:209]
	v_pk_add_f32 v[10:11], v[10:11], v[206:207]
	v_pk_add_f32 v[8:9], v[8:9], v[212:213]
	v_pk_add_f32 v[6:7], v[6:7], v[210:211]
	v_pk_add_f32 v[4:5], v[4:5], v[216:217]
	v_pk_add_f32 v[2:3], v[2:3], v[214:215]
	v_cvt_pk_bf16_f32 v18, v18, v19
	v_cvt_pk_bf16_f32 v19, v20, v21
	v_cvt_pk_bf16_f32 v10, v10, v11
	v_cvt_pk_bf16_f32 v11, v12, v13
	v_cvt_pk_bf16_f32 v6, v6, v7
	v_cvt_pk_bf16_f32 v7, v8, v9
	v_cvt_pk_bf16_f32 v2, v2, v3
	v_cvt_pk_bf16_f32 v3, v4, v5
	ds_bpermute_b32 v202, v244, v18
	ds_bpermute_b32 v203, v244, v19
	ds_bpermute_b32 v204, v244, v10
	ds_bpermute_b32 v205, v244, v11
	ds_bpermute_b32 v206, v245, v18
	ds_bpermute_b32 v207, v245, v19
	ds_bpermute_b32 v208, v245, v10
	ds_bpermute_b32 v209, v245, v11
	s_waitcnt lgkmcnt(0)
	v_cndmask_b32_e64 v202, v202, v204, s[98:99]
	v_cndmask_b32_e64 v203, v203, v205, s[98:99]
	v_add_u32_e32 v204, 0x58000, v246
	global_store_dwordx2 v204, v[202:203], s[48:49]
	v_cndmask_b32_e64 v206, v206, v208, s[98:99]
	v_cndmask_b32_e64 v207, v207, v209, s[98:99]
	v_add_u32_e32 v208, 0x5c000, v246
	global_store_dwordx2 v208, v[206:207], s[48:49]
	ds_bpermute_b32 v202, v244, v6
	ds_bpermute_b32 v203, v244, v7
	ds_bpermute_b32 v204, v244, v2
	ds_bpermute_b32 v205, v244, v3
	ds_bpermute_b32 v206, v245, v6
	ds_bpermute_b32 v207, v245, v7
	ds_bpermute_b32 v208, v245, v2
	ds_bpermute_b32 v209, v245, v3
	s_waitcnt lgkmcnt(0)
	v_cndmask_b32_e64 v202, v202, v204, s[98:99]
	v_cndmask_b32_e64 v203, v203, v205, s[98:99]
	v_add_u32_e32 v204, 0x58000, v246
	global_store_dwordx2 v204, v[202:203], s[48:49] offset:256
	v_cndmask_b32_e64 v206, v206, v208, s[98:99]
	v_cndmask_b32_e64 v207, v207, v209, s[98:99]
	v_add_u32_e32 v208, 0x5c000, v246
	global_store_dwordx2 v208, v[206:207], s[48:49] offset:256
	s_and_b64 vcc, exec, s[20:21]
	s_mov_b32 s42, s40
	s_mov_b32 s43, s41
	s_mov_b64 s[22:23], 0x2c000
	s_cbranch_vccz .LBB0_1006
	s_waitcnt vmcnt(0)
	s_cmpk_gt_u32 s3, 0xff
	s_cbranch_scc1 .LBB0_1011
	s_barrier

; DI float bflo(unsigned u) { return __uint_as_float(u << 16); }
; DI float bfhi(unsigned u) { return __uint_as_float(u & 0xffff0000u); }
; DI void phase_norm1(const Params& p) {
;     const int lane = threadIdx.x & 63, gw = blockIdx.x * 8 + (threadIdx.x >> 6), nw = gridDim.x * 8;
;     bf16_t* x1 = (bf16_t*)(p.ws + WS_X1); const float* part = (const float*)(p.ws + WS_PART1); bf16_t* out = (bf16_t*)(p.ws + WS_XN); const float* w = p.norm_w + 1024;
;     for (int tok = gw; tok < T_TOK; tok += nw) {
;         f32x4 v[4]; float ss = 0.f;
; #pragma unroll
;         for (int i = 0; i < 4; ++i) { const int c = 4 * lane + 256 * i;
;             if (tok < T_PR) { const u32x2 t = *(const u32x2*)(x1 + (size_t)tok * 1024 + c); v[i] = (f32x4){bflo(t.x), bfhi(t.x), bflo(t.y), bfhi(t.y)}; }
.LBB0_1095:
	s_cmp_lt_i32 s80, 7
	s_cselect_b64 s[6:7], -1, 0
	s_and_b64 s[0:1], s[6:7], s[0:1]
	s_and_b64 s[0:1], s[44:45], s[0:1]
	v_lshlrev_b32_e32 v164, 2, v152
	v_lshlrev_b32_e32 v166, 1, v152
	s_and_saveexec_b64 s[8:9], s[0:1]
	s_cbranch_execz .LBB0_1114
	v_lshlrev_b32_e32 v2, 3, v196
	v_lshlrev_b32_e32 v3, 4, v196
	s_add_u32 s10, s70, 0x1000
	s_addc_u32 s11, s71, 0
	s_add_u32 s12, s78, 0xc480000
	s_addc_u32 s13, s79, 0
	s_add_u32 s16, s78, 0x1a80000
	s_addc_u32 s17, s79, 0
	global_load_dwordx4 v[16:19], v3, s[10:11] nt
	global_load_dwordx4 v[20:23], v3, s[10:11] offset:1024 nt
	global_load_dwordx4 v[24:27], v3, s[10:11] offset:2048 nt
	global_load_dwordx4 v[28:31], v3, s[10:11] offset:3072 nt
	v_readfirstlane_b32 s4, v162
	s_mov_b32 s23, 0
	v_mov_b32_e32 v60, 0x358637bd
	s_cmp_lt_u32 s4, 0x4000
	s_cbranch_scc0 .Ln1_sample
	s_lshl_b32 s5, s4, 11
	v_add_u32_e32 v4, s5, v2
	global_load_dwordx2 v[32:33], v4, s[12:13] nt
	global_load_dwordx2 v[34:35], v4, s[12:13] offset:512 nt
	global_load_dwordx2 v[36:37], v4, s[12:13] offset:1024 nt
	global_load_dwordx2 v[38:39], v4, s[12:13] offset:1536 nt
.Ln1_a:
	s_add_u32 s22, s4, s46
	s_cmp_lt_u32 s22, 0x4000
	s_cbranch_scc0 .Ln1_a_nonext
	s_lshl_b32 s5, s22, 11
	v_add_u32_e32 v5, s5, v2
	global_load_dwordx2 v[40:41], v5, s[12:13] nt
	global_load_dwordx2 v[42:43], v5, s[12:13] offset:512 nt
	global_load_dwordx2 v[44:45], v5, s[12:13] offset:1024 nt
	global_load_dwordx2 v[46:47], v5, s[12:13] offset:1536 nt
	s_cmp_eq_u32 s23, 0
	s_cbranch_scc1 .Ln1_a_w4
	s_waitcnt vmcnt(8)
	s_branch .Ln1_a_have

; DI float bflo(unsigned u) { return __uint_as_float(u << 16); }
; DI float bfhi(unsigned u) { return __uint_as_float(u & 0xffff0000u); }
; DI void phase_norm1(const Params& p) {
;     ...
;     for (int tok = gw; tok < T_TOK; tok += nw) {
;         f32x4 v[4]; float ss = 0.f;
; #pragma unroll
;         for (int i = 0; i < 4; ++i) { const int c = 4 * lane + 256 * i;
;             if (tok < T_PR) { const u32x2 t = *(const u32x2*)(x1 + (size_t)tok * 1024 + c); v[i] = (f32x4){bflo(t.x), bfhi(t.x), bflo(t.y), bfhi(t.y)}; }
.Ln1_b:
	s_add_u32 s22, s4, s46
	s_cmp_lt_u32 s22, 0x4000
	s_cbranch_scc0 .Ln1_b_nonext
	s_lshl_b32 s5, s22, 11
	v_add_u32_e32 v5, s5, v2
	global_load_dwordx2 v[32:33], v5, s[12:13] nt
	global_load_dwordx2 v[34:35], v5, s[12:13] offset:512 nt
	global_load_dwordx2 v[36:37], v5, s[12:13] offset:1024 nt
	global_load_dwordx2 v[38:39], v5, s[12:13] offset:1536 nt
	s_cmp_eq_u32 s23, 0
	s_cbranch_scc1 .Ln1_b_w4
	s_waitcnt vmcnt(8)
	s_branch .Ln1_b_have

; DI unsigned pk_bf16(float a, float b) { f32x2 v = {a, b}; bf2_t r = __builtin_convertvector(v, bf2_t); return __builtin_bit_cast(unsigned, r); }
; DI void phase_norm1(const Params& p) {
;     ...
;             else { const size_t o = (size_t)(tok - T_PR) * 1024 + c; v[i] = *(const f32x4*)(p.xs + o);
; #pragma unroll
;                 for (int s = 0; s < 4; ++s) v[i] += *(const f32x4*)(part + (size_t)s * 1048576 + o);
;                 u32x2 t; t.x = pk_bf16(v[i].x, v[i].y); t.y = pk_bf16(v[i].z, v[i].w); *(u32x2*)(x1 + (size_t)tok * 1024 + c) = t; }
;             ss += v[i].x * v[i].x + v[i].y * v[i].y + v[i].z * v[i].z + v[i].w * v[i].w; }
;         ss = wave_sum(ss);
;         const float rstd = rsqrtf(ss * (1.f / 1024.f) + 1e-6f);
; #pragma unroll
;         for (int i = 0; i < 4; ++i) { const f32x4 ww = *(const f32x4*)(w + 4 * lane + 256 * i);
;             u32x2 o; o.x = pk_bf16(v[i].x * rstd * ww.x, v[i].y * rstd * ww.y); o.y = pk_bf16(v[i].z * rstd * ww.z, v[i].w * rstd * ww.w);
;             *(u32x2*)(out + (size_t)tok * 1024 + 4 * lane + 256 * i) = o; }
.Ln1_sample:
	s_cmp_lt_u32 s4, 0x4400
	s_cbranch_scc0 .Ln1_done
	s_sub_u32 s5, s4, 0x4000
	s_lshl_b32 s5, s5, 12
	s_add_u32 s24, s62, s5
	s_addc_u32 s25, s63, 0
	global_load_dwordx4 v[64:67], v3, s[24:25] nt
	global_load_dwordx4 v[68:71], v3, s[24:25] offset:1024 nt
	global_load_dwordx4 v[72:75], v3, s[24:25] offset:2048 nt
	global_load_dwordx4 v[76:79], v3, s[24:25] offset:3072 nt
	s_add_u32 s24, s78, 0x26500000
	s_addc_u32 s25, s79, 0
	s_add_u32 s24, s24, s5
	s_addc_u32 s25, s25, 0
	global_load_dwordx4 v[80:83], v3, s[24:25] nt
	global_load_dwordx4 v[84:87], v3, s[24:25] offset:1024 nt
	global_load_dwordx4 v[88:91], v3, s[24:25] offset:2048 nt
	global_load_dwordx4 v[92:95], v3, s[24:25] offset:3072 nt
	s_add_u32 s24, s24, 0x400000
	s_addc_u32 s25, s25, 0
	global_load_dwordx4 v[96:99], v3, s[24:25] nt
	global_load_dwordx4 v[100:103], v3, s[24:25] offset:1024 nt
	global_load_dwordx4 v[104:107], v3, s[24:25] offset:2048 nt
	global_load_dwordx4 v[108:111], v3, s[24:25] offset:3072 nt
	s_add_u32 s24, s24, 0x400000
	s_addc_u32 s25, s25, 0
	global_load_dwordx4 v[112:115], v3, s[24:25] nt
	global_load_dwordx4 v[116:119], v3, s[24:25] offset:1024 nt
	global_load_dwordx4 v[120:123], v3, s[24:25] offset:2048 nt
	global_load_dwordx4 v[124:127], v3, s[24:25] offset:3072 nt
	s_add_u32 s24, s24, 0x400000
	s_addc_u32 s25, s25, 0
	global_load_dwordx4 v[128:131], v3, s[24:25] nt
	global_load_dwordx4 v[132:135], v3, s[24:25] offset:1024 nt
	global_load_dwordx4 v[136:139], v3, s[24:25] offset:2048 nt
	global_load_dwordx4 v[140:143], v3, s[24:25] offset:3072 nt
	s_waitcnt vmcnt(0)
	v_add_f32_e32 v64, v64, v80
	v_add_f32_e32 v65, v65, v81
	v_add_f32_e32 v66, v66, v82
	v_add_f32_e32 v67, v67, v83
	v_add_f32_e32 v68, v68, v84
	v_add_f32_e32 v69, v69, v85
	v_add_f32_e32 v70, v70, v86
	v_add_f32_e32 v71, v71, v87
	v_add_f32_e32 v72, v72, v88
	v_add_f32_e32 v73, v73, v89
	v_add_f32_e32 v74, v74, v90
	v_add_f32_e32 v75, v75, v91
	v_add_f32_e32 v76, v76, v92
	v_add_f32_e32 v77, v77, v93
	v_add_f32_e32 v78, v78, v94
	v_add_f32_e32 v79, v79, v95
	v_add_f32_e32 v64, v64, v96
	v_add_f32_e32 v65, v65, v97
	v_add_f32_e32 v66, v66, v98
	v_add_f32_e32 v67, v67, v99
	v_add_f32_e32 v68, v68, v100
	v_add_f32_e32 v69, v69, v101
	v_add_f32_e32 v70, v70, v102
	v_add_f32_e32 v71, v71, v103
	v_add_f32_e32 v72, v72, v104
	v_add_f32_e32 v73, v73, v105
	v_add_f32_e32 v74, v74, v106
	v_add_f32_e32 v75, v75, v107
	v_add_f32_e32 v76, v76, v108
	v_add_f32_e32 v77, v77, v109
	v_add_f32_e32 v78, v78, v110
	v_add_f32_e32 v79, v79, v111
	v_add_f32_e32 v64, v64, v112
	v_add_f32_e32 v65, v65, v113
	v_add_f32_e32 v66, v66, v114
	v_add_f32_e32 v67, v67, v115
	v_add_f32_e32 v68, v68, v116
	v_add_f32_e32 v69, v69, v117
	v_add_f32_e32 v70, v70, v118
	v_add_f32_e32 v71, v71, v119
	v_add_f32_e32 v72, v72, v120
	v_add_f32_e32 v73, v73, v121
	v_add_f32_e32 v74, v74, v122
	v_add_f32_e32 v75, v75, v123
	v_add_f32_e32 v76, v76, v124
	v_add_f32_e32 v77, v77, v125
	v_add_f32_e32 v78, v78, v126
	v_add_f32_e32 v79, v79, v127
	v_add_f32_e32 v64, v64, v128
	v_add_f32_e32 v65, v65, v129
	v_add_f32_e32 v66, v66, v130
	v_add_f32_e32 v67, v67, v131
	v_add_f32_e32 v68, v68, v132
	v_add_f32_e32 v69, v69, v133
	v_add_f32_e32 v70, v70, v134
	v_add_f32_e32 v71, v71, v135
	v_add_f32_e32 v72, v72, v136
	v_add_f32_e32 v73, v73, v137
	v_add_f32_e32 v74, v74, v138
	v_add_f32_e32 v75, v75, v139
	v_add_f32_e32 v76, v76, v140
	v_add_f32_e32 v77, v77, v141
	v_add_f32_e32 v78, v78, v142
	v_add_f32_e32 v79, v79, v143
	s_lshl_b32 s26, s4, 11
	s_add_u32 s26, s12, s26
	s_addc_u32 s27, s13, 0
	v_cvt_pk_bf16_f32 v144, v64, v65
	v_cvt_pk_bf16_f32 v145, v66, v67
	global_store_dwordx2 v2, v[144:145], s[26:27]
	v_cvt_pk_bf16_f32 v146, v68, v69
	v_cvt_pk_bf16_f32 v147, v70, v71
	global_store_dwordx2 v2, v[146:147], s[26:27] offset:512
	v_cvt_pk_bf16_f32 v148, v72, v73
	v_cvt_pk_bf16_f32 v149, v74, v75
	global_store_dwordx2 v2, v[148:149], s[26:27] offset:1024
	v_cvt_pk_bf16_f32 v150, v76, v77
	v_cvt_pk_bf16_f32 v151, v78, v79
	global_store_dwordx2 v2, v[150:151], s[26:27] offset:1536
	v_mul_f32_e32 v48, v64, v64
	v_fmac_f32_e32 v48, v65, v65
	v_fmac_f32_e32 v48, v66, v66
	v_fmac_f32_e32 v48, v67, v67
	v_mul_f32_e32 v49, v68, v68
	v_fmac_f32_e32 v49, v69, v69
	v_fmac_f32_e32 v49, v70, v70
	v_fmac_f32_e32 v49, v71, v71
	v_mul_f32_e32 v50, v72, v72
	v_fmac_f32_e32 v50, v73, v73
	v_fmac_f32_e32 v50, v74, v74
	v_fmac_f32_e32 v50, v75, v75
	v_mul_f32_e32 v51, v76, v76
	v_fmac_f32_e32 v51, v77, v77
	v_fmac_f32_e32 v51, v78, v78
	v_fmac_f32_e32 v51, v79, v79
	v_add_f32_e32 v48, v48, v49
	v_add_f32_e32 v50, v50, v51
	v_add_f32_e32 v48, v48, v50
	s_nop 1
	v_add_f32_dpp v48, v48, v48 quad_perm:[1,0,3,2] row_mask:0xf bank_mask:0xf bound_ctrl:1
	s_nop 1
	v_add_f32_dpp v48, v48, v48 quad_perm:[2,3,0,1] row_mask:0xf bank_mask:0xf bound_ctrl:1
	s_nop 1
	v_add_f32_dpp v48, v48, v48 row_ror:4 row_mask:0xf bank_mask:0xf bound_ctrl:1
	s_nop 1
	v_add_f32_dpp v48, v48, v48 row_ror:8 row_mask:0xf bank_mask:0xf bound_ctrl:1
	s_nop 1
	v_readlane_b32 s28, v48, 0
	v_readlane_b32 s29, v48, 16
	v_readlane_b32 s30, v48, 32
	v_readlane_b32 s31, v48, 48
	s_nop 1
	v_mov_b32_e32 v52, s28
	v_add_f32_e32 v52, s29, v52
	v_add_f32_e32 v52, s30, v52
	v_add_f32_e32 v52, s31, v52
	v_fmamk_f32 v52, v52, 0x3a800000, v60
	v_rsq_f32_e32 v52, v52
	s_lshl_b32 s20, s4, 11
	s_add_u32 s20, s16, s20
	s_addc_u32 s21, s17, 0
	v_mul_f32_e32 v64, v64, v52
	v_mul_f32_e32 v65, v65, v52
	v_mul_f32_e32 v66, v66, v52
	v_mul_f32_e32 v67, v67, v52
	v_mul_f32_e32 v64, v64, v16
	v_mul_f32_e32 v65, v65, v17
	v_mul_f32_e32 v66, v66, v18
	v_mul_f32_e32 v67, v67, v19
	v_cvt_pk_bf16_f32 v64, v64, v65
	v_cvt_pk_bf16_f32 v65, v66, v67
	global_store_dwordx2 v2, v[64:65], s[20:21]
	v_mul_f32_e32 v68, v68, v52
	v_mul_f32_e32 v69, v69, v52
	v_mul_f32_e32 v70, v70, v52
	v_mul_f32_e32 v71, v71, v52
	v_mul_f32_e32 v68, v68, v20
	v_mul_f32_e32 v69, v69, v21
	v_mul_f32_e32 v70, v70, v22
	v_mul_f32_e32 v71, v71, v23
	v_cvt_pk_bf16_f32 v68, v68, v69
	v_cvt_pk_bf16_f32 v69, v70, v71
	global_store_dwordx2 v2, v[68:69], s[20:21] offset:512
	v_mul_f32_e32 v72, v72, v52
	v_mul_f32_e32 v73, v73, v52
	v_mul_f32_e32 v74, v74, v52
	v_mul_f32_e32 v75, v75, v52
	v_mul_f32_e32 v72, v72, v24
	v_mul_f32_e32 v73, v73, v25
	v_mul_f32_e32 v74, v74, v26
	v_mul_f32_e32 v75, v75, v27
	v_cvt_pk_bf16_f32 v72, v72, v73
	v_cvt_pk_bf16_f32 v73, v74, v75
	global_store_dwordx2 v2, v[72:73], s[20:21] offset:1024
	v_mul_f32_e32 v76, v76, v52
	v_mul_f32_e32 v77, v77, v52
	v_mul_f32_e32 v78, v78, v52
	v_mul_f32_e32 v79, v79, v52
	v_mul_f32_e32 v76, v76, v28
	v_mul_f32_e32 v77, v77, v29
	v_mul_f32_e32 v78, v78, v30
	v_mul_f32_e32 v79, v79, v31
	v_cvt_pk_bf16_f32 v76, v76, v77
	v_cvt_pk_bf16_f32 v77, v78, v79
	global_store_dwordx2 v2, v[76:77], s[20:21] offset:1536

; #define PG8_STAGE(bufoff, gbase, voff) do { _Pragma("unroll") for (int _i = 0; _i < 2; ++_i) \
;         __builtin_amdgcn_global_load_lds((const unsigned*)((const char*)(gbase) + (voff)[_i]), (LAS unsigned*)(lds + (bufoff) + ldsw + _i * 8192), 16, 0, 0); } while (0)
; #define PG8_LDA(dst, b, h) do { _Pragma("unroll") for (int m = 0; m < 4; ++m) _Pragma("unroll") for (int k = 0; k < 2; ++k) dst[m][k] = *(const LAS bf16x8*)(lds + PG8_SA(b, h) + aoff + m * 2048 + k * 1024); } while (0)
; #define PG8_LDB(dst, b, h) do { _Pragma("unroll") for (int n = 0; n < 2; ++n) _Pragma("unroll") for (int k = 0; k < 2; ++k) dst[n][k] = *(const LAS bf16x8*)(lds + PG8_SB(b, h) + boff + n * 2048 + k * 1024); } while (0)
; #define PG8_MMA(ai, bj, At, Bt) do { __builtin_amdgcn_s_setprio(1); _Pragma("unroll") for (int m = 0; m < 4; ++m) _Pragma("unroll") for (int n = 0; n < 2; ++n) _Pragma("unroll") for (int k = 0; k < 2; ++k) \
;         acc[ai][bj][m][n] = __builtin_amdgcn_mfma_f32_16x16x32_bf16(Bt[n][k], At[m][k], acc[ai][bj][m][n], 0, 0, 0); __builtin_amdgcn_s_setprio(0); } while (0)
; #define PG8_WAIT_L(n) asm volatile("s_waitcnt lgkmcnt(" #n ")" ::: "memory")
; #define PG8_BAR __builtin_amdgcn_s_barrier()
; #define PG8_SCHED __builtin_amdgcn_sched_barrier(0)
; template <class Epi, class Sched>
; DI void gemm_phase(LAS unsigned char* lds, const Gemm g, const Sched& S, const Epi& E) {
;     ...
;             PG8_LDB(B0, 0, 0); PG8_SCHED; PG8_LDA(At, 0, 0); PG8_STAGE(PG8_SA(1, 1), a1 + hstep, voffA);
;             PG8_WAIT_L(8); PG8_BAR; PG8_WAIT_L(0); PG8_MMA(0, 0, At, B0); PG8_BAR; PG8_SCHED;
;             PG8_LDB(B1, 0, 1); PG8_STAGE(PG8_SB(0, 0), b2, voffB);
;             PG8_BAR; PG8_WAIT_L(0); PG8_MMA(0, 1, At, B1); PG8_BAR;
;             PG8_LDA(At, 0, 1); PG8_STAGE(PG8_SA(0, 0), a2, voffA);
;             PG8_BAR; PG8_WAIT_L(0); PG8_MMA(1, 0, At, B0); PG8_BAR; PG8_SCHED;
.LBB0_1523:
	ds_read_b128 v[140:143], v146
	ds_read_b128 v[150:153], v146 offset:1024
	ds_read_b128 v[154:157], v146 offset:2048
	ds_read_b128 v[158:161], v146 offset:3072
	s_add_u32 s50, s42, 0xfff80080
	s_addc_u32 s51, s43, -1
	s_cmp_eq_u32 s73, 28
	s_cselect_b32 s53, s67, s51
	s_cselect_b32 s52, s68, s50
	s_cselect_b32 s51, s69, s72
	s_cselect_b32 s50, s70, s71
	v_lshl_add_u64 v[202:203], s[42:43], 0, v[136:137]
	s_add_i32 m0, s47, 0xc000
	ds_read_b128 v[168:171], v147
	ds_read_b128 v[172:175], v147 offset:1024
	ds_read_b128 v[176:179], v147 offset:2048
	ds_read_b128 v[180:183], v147 offset:3072
	ds_read_b128 v[184:187], v147 offset:4096
	ds_read_b128 v[188:191], v147 offset:5120
	ds_read_b128 v[192:195], v147 offset:6144
	ds_read_b128 v[198:201], v147 offset:7168
	global_load_lds_dwordx4 v[202:203], off
	v_lshl_add_u64 v[202:203], s[42:43], 0, v[138:139]
	s_add_i32 m0, s47, 0xe000
	s_nop 0
	global_load_lds_dwordx4 v[202:203], off
	s_waitcnt lgkmcnt(8)
	s_barrier
	s_waitcnt lgkmcnt(0)
	s_setprio 1
	s_waitcnt lgkmcnt(0)
	v_mfma_f32_16x16x32_bf16 v[126:129], v[140:143], v[168:171], v[126:129]
	v_mfma_f32_16x16x32_bf16 v[122:125], v[154:157], v[168:171], v[122:125]
	v_mfma_f32_16x16x32_bf16 v[110:113], v[140:143], v[176:179], v[110:113]
	v_mfma_f32_16x16x32_bf16 v[106:109], v[154:157], v[176:179], v[106:109]
	v_mfma_f32_16x16x32_bf16 v[94:97], v[140:143], v[184:187], v[94:97]
	v_mfma_f32_16x16x32_bf16 v[90:93], v[154:157], v[184:187], v[90:93]
	v_mfma_f32_16x16x32_bf16 v[78:81], v[140:143], v[192:195], v[78:81]
	v_mfma_f32_16x16x32_bf16 v[74:77], v[154:157], v[192:195], v[74:77]
	v_mfma_f32_16x16x32_bf16 v[126:129], v[150:153], v[172:175], v[126:129]
	v_mfma_f32_16x16x32_bf16 v[122:125], v[158:161], v[172:175], v[122:125]
	v_mfma_f32_16x16x32_bf16 v[110:113], v[150:153], v[180:183], v[110:113]
	v_mfma_f32_16x16x32_bf16 v[106:109], v[158:161], v[180:183], v[106:109]
	v_mfma_f32_16x16x32_bf16 v[94:97], v[150:153], v[188:191], v[94:97]
	v_mfma_f32_16x16x32_bf16 v[90:93], v[158:161], v[188:191], v[90:93]
	v_mfma_f32_16x16x32_bf16 v[78:81], v[150:153], v[198:201], v[78:81]
	v_mfma_f32_16x16x32_bf16 v[74:77], v[158:161], v[198:201], v[74:77]
	s_setprio 0
	s_barrier
	s_add_i32 s83, s63, s33
	v_lshl_add_u64 v[218:219], s[50:51], 0, v[132:133]
	s_mov_b32 m0, s83
	ds_read_b128 v[202:205], v148
	ds_read_b128 v[206:209], v148 offset:1024
	ds_read_b128 v[210:213], v148 offset:2048
	ds_read_b128 v[214:217], v148 offset:3072
	global_load_lds_dwordx4 v[218:219], off
	v_lshl_add_u64 v[220:221], s[50:51], 0, v[130:131]
	s_add_i32 m0, s83, 0x2000
	s_nop 0
	global_load_lds_dwordx4 v[220:221], off
	s_barrier
	s_waitcnt lgkmcnt(0)
	s_setprio 1
	s_waitcnt lgkmcnt(0)
	v_mfma_f32_16x16x32_bf16 v[118:121], v[202:205], v[168:171], v[118:121]
	v_mfma_f32_16x16x32_bf16 v[114:117], v[210:213], v[168:171], v[114:117]
	v_mfma_f32_16x16x32_bf16 v[102:105], v[202:205], v[176:179], v[102:105]
	v_mfma_f32_16x16x32_bf16 v[98:101], v[210:213], v[176:179], v[98:101]
	v_mfma_f32_16x16x32_bf16 v[86:89], v[202:205], v[184:187], v[86:89]
	v_mfma_f32_16x16x32_bf16 v[82:85], v[210:213], v[184:187], v[82:85]
	v_mfma_f32_16x16x32_bf16 v[70:73], v[202:205], v[192:195], v[70:73]
	v_mfma_f32_16x16x32_bf16 v[66:69], v[210:213], v[192:195], v[66:69]
	v_mfma_f32_16x16x32_bf16 v[118:121], v[206:209], v[172:175], v[118:121]
	v_mfma_f32_16x16x32_bf16 v[114:117], v[214:217], v[172:175], v[114:117]
	v_mfma_f32_16x16x32_bf16 v[102:105], v[206:209], v[180:183], v[102:105]
	v_mfma_f32_16x16x32_bf16 v[98:101], v[214:217], v[180:183], v[98:101]
	v_mfma_f32_16x16x32_bf16 v[86:89], v[206:209], v[188:191], v[86:89]
	v_mfma_f32_16x16x32_bf16 v[82:85], v[214:217], v[188:191], v[82:85]
	v_mfma_f32_16x16x32_bf16 v[70:73], v[206:209], v[198:201], v[70:73]
	v_mfma_f32_16x16x32_bf16 v[66:69], v[214:217], v[198:201], v[66:69]
	s_setprio 0
	s_mov_b32 m0, s47
	v_lshl_add_u64 v[222:223], s[52:53], 0, v[132:133]
	s_barrier
	ds_read_b128 v[168:171], v147 offset:16384
	ds_read_b128 v[172:175], v147 offset:17408
	ds_read_b128 v[176:179], v147 offset:18432
	ds_read_b128 v[180:183], v147 offset:19456
	ds_read_b128 v[184:187], v147 offset:20480
	ds_read_b128 v[188:191], v147 offset:21504
	ds_read_b128 v[192:195], v147 offset:22528
	ds_read_b128 v[198:201], v147 offset:23552
	global_load_lds_dwordx4 v[222:223], off
	v_lshl_add_u64 v[224:225], s[52:53], 0, v[130:131]
	s_mov_b32 m0, s54
	s_nop 0
	global_load_lds_dwordx4 v[224:225], off
	s_barrier
	s_waitcnt lgkmcnt(0)
	s_setprio 1
	s_waitcnt lgkmcnt(0)
	v_mfma_f32_16x16x32_bf16 v[62:65], v[140:143], v[168:171], v[62:65]
	v_mfma_f32_16x16x32_bf16 v[58:61], v[154:157], v[168:171], v[58:61]
	v_mfma_f32_16x16x32_bf16 v[46:49], v[140:143], v[176:179], v[46:49]
	v_mfma_f32_16x16x32_bf16 v[42:45], v[154:157], v[176:179], v[42:45]
	v_mfma_f32_16x16x32_bf16 v[30:33], v[140:143], v[184:187], v[30:33]
	v_mfma_f32_16x16x32_bf16 v[26:29], v[154:157], v[184:187], v[26:29]
	v_mfma_f32_16x16x32_bf16 v[14:17], v[140:143], v[192:195], v[14:17]
	v_mfma_f32_16x16x32_bf16 v[10:13], v[154:157], v[192:195], v[10:13]
	v_mfma_f32_16x16x32_bf16 v[62:65], v[150:153], v[172:175], v[62:65]
	v_mfma_f32_16x16x32_bf16 v[58:61], v[158:161], v[172:175], v[58:61]
	v_mfma_f32_16x16x32_bf16 v[46:49], v[150:153], v[180:183], v[46:49]
	v_mfma_f32_16x16x32_bf16 v[42:45], v[158:161], v[180:183], v[42:45]
	v_mfma_f32_16x16x32_bf16 v[30:33], v[150:153], v[188:191], v[30:33]
	v_mfma_f32_16x16x32_bf16 v[26:29], v[158:161], v[188:191], v[26:29]
	v_mfma_f32_16x16x32_bf16 v[14:17], v[150:153], v[198:201], v[14:17]
	v_mfma_f32_16x16x32_bf16 v[10:13], v[158:161], v[198:201], v[10:13]
	s_setprio 0
	s_barrier
; #define PG8_STAGE(bufoff, gbase, voff) do { _Pragma("unroll") for (int _i = 0; _i < 2; ++_i) \
;         __builtin_amdgcn_global_load_lds((const unsigned*)((const char*)(gbase) + (voff)[_i]), (LAS unsigned*)(lds + (bufoff) + ldsw + _i * 8192), 16, 0, 0); } while (0)
; #define PG8_LDA(dst, b, h) do { _Pragma("unroll") for (int m = 0; m < 4; ++m) _Pragma("unroll") for (int k = 0; k < 2; ++k) dst[m][k] = *(const LAS bf16x8*)(lds + PG8_SA(b, h) + aoff + m * 2048 + k * 1024); } while (0)
; #define PG8_LDB(dst, b, h) do { _Pragma("unroll") for (int n = 0; n < 2; ++n) _Pragma("unroll") for (int k = 0; k < 2; ++k) dst[n][k] = *(const LAS bf16x8*)(lds + PG8_SB(b, h) + boff + n * 2048 + k * 1024); } while (0)
; #define PG8_MMA(ai, bj, At, Bt) do { __builtin_amdgcn_s_setprio(1); _Pragma("unroll") for (int m = 0; m < 4; ++m) _Pragma("unroll") for (int n = 0; n < 2; ++n) _Pragma("unroll") for (int k = 0; k < 2; ++k) \
;         acc[ai][bj][m][n] = __builtin_amdgcn_mfma_f32_16x16x32_bf16(Bt[n][k], At[m][k], acc[ai][bj][m][n], 0, 0, 0); __builtin_amdgcn_s_setprio(0); } while (0)
; #define PG8_WAIT_V(n) asm volatile("s_waitcnt vmcnt(" #n ")" ::: "memory")
; #define PG8_WAIT_L(n) asm volatile("s_waitcnt lgkmcnt(" #n ")" ::: "memory")
; #define PG8_BAR __builtin_amdgcn_s_barrier()
; #define PG8_SCHED __builtin_amdgcn_sched_barrier(0)
; template <class Epi, class Sched>
; DI void gemm_phase(LAS unsigned char* lds, const Gemm g, const Sched& S, const Epi& E) {
;     ...
;             PG8_STAGE(PG8_SB(0, 1), b2 + hstep, voffB);
;             PG8_WAIT_V(6); PG8_BAR; PG8_MMA(1, 1, At, B1); PG8_BAR;
;             PG8_LDB(B0, 1, 0); PG8_SCHED; PG8_LDA(At, 1, 0); PG8_STAGE(PG8_SA(0, 1), a2 + hstep, voffA);
;             PG8_WAIT_L(8); PG8_BAR; PG8_WAIT_L(0); PG8_MMA(0, 0, At, B0); PG8_BAR; PG8_SCHED;
;             PG8_LDB(B1, 1, 1); PG8_STAGE(PG8_SB(1, 0), b3, voffB);
;             PG8_BAR; PG8_WAIT_L(0); PG8_MMA(0, 1, At, B1); PG8_BAR;
	s_add_u32 s88, s50, 0x80000
	s_addc_u32 s89, s51, 0
	s_add_i32 s83, s64, s33
	v_lshl_add_u64 v[140:141], s[88:89], 0, v[132:133]
	s_mov_b32 m0, s83
	s_nop 0
	global_load_lds_dwordx4 v[140:141], off
	v_lshl_add_u64 v[140:141], s[88:89], 0, v[130:131]
	s_add_i32 m0, s83, 0x2000
	s_nop 0
	global_load_lds_dwordx4 v[140:141], off
	s_waitcnt vmcnt(6)
	s_barrier
	s_setprio 1
	v_mfma_f32_16x16x32_bf16 v[54:57], v[202:205], v[168:171], v[54:57]
	v_mfma_f32_16x16x32_bf16 v[50:53], v[210:213], v[168:171], v[50:53]
	v_mfma_f32_16x16x32_bf16 v[38:41], v[202:205], v[176:179], v[38:41]
	v_mfma_f32_16x16x32_bf16 v[34:37], v[210:213], v[176:179], v[34:37]
	v_mfma_f32_16x16x32_bf16 v[22:25], v[202:205], v[184:187], v[22:25]
	v_mfma_f32_16x16x32_bf16 v[18:21], v[210:213], v[184:187], v[18:21]
	v_mfma_f32_16x16x32_bf16 v[6:9], v[202:205], v[192:195], v[6:9]
	v_mfma_f32_16x16x32_bf16 v[2:5], v[210:213], v[192:195], v[2:5]
	v_mfma_f32_16x16x32_bf16 v[54:57], v[206:209], v[172:175], v[54:57]
	v_mfma_f32_16x16x32_bf16 v[50:53], v[214:217], v[172:175], v[50:53]
	v_mfma_f32_16x16x32_bf16 v[38:41], v[206:209], v[180:183], v[38:41]
	v_mfma_f32_16x16x32_bf16 v[34:37], v[214:217], v[180:183], v[34:37]
	v_mfma_f32_16x16x32_bf16 v[22:25], v[206:209], v[188:191], v[22:25]
	v_mfma_f32_16x16x32_bf16 v[18:21], v[214:217], v[188:191], v[18:21]
	v_mfma_f32_16x16x32_bf16 v[6:9], v[206:209], v[198:201], v[6:9]
	v_mfma_f32_16x16x32_bf16 v[2:5], v[214:217], v[198:201], v[2:5]
	s_setprio 0
	s_add_i32 s83, 0, 0x18000
	v_add_u32_e32 v134, s83, v145
	s_barrier
	ds_read_b128 v[140:143], v134
	ds_read_b128 v[150:153], v134 offset:1024
	ds_read_b128 v[154:157], v134 offset:2048
	ds_read_b128 v[158:161], v134 offset:3072
	s_add_u32 s52, s52, 0x80000
	s_addc_u32 s53, s53, 0
	s_mov_b32 m0, s55
	v_lshl_add_u64 v[202:203], s[52:53], 0, v[132:133]
	ds_read_b128 v[168:171], v147 offset:32768
	ds_read_b128 v[172:175], v147 offset:33792
	ds_read_b128 v[176:179], v147 offset:34816
	ds_read_b128 v[180:183], v147 offset:35840
	ds_read_b128 v[184:187], v147 offset:36864
	ds_read_b128 v[188:191], v147 offset:37888
	ds_read_b128 v[192:195], v147 offset:38912
	ds_read_b128 v[198:201], v147 offset:39936
	global_load_lds_dwordx4 v[202:203], off
	v_lshl_add_u64 v[202:203], s[52:53], 0, v[130:131]
	s_mov_b32 m0, s57
	s_nop 0
	global_load_lds_dwordx4 v[202:203], off
	s_waitcnt lgkmcnt(8)
	s_barrier
	s_waitcnt lgkmcnt(0)
	s_setprio 1
	s_waitcnt lgkmcnt(0)
	v_mfma_f32_16x16x32_bf16 v[126:129], v[140:143], v[168:171], v[126:129]
	v_mfma_f32_16x16x32_bf16 v[122:125], v[154:157], v[168:171], v[122:125]
	v_mfma_f32_16x16x32_bf16 v[110:113], v[140:143], v[176:179], v[110:113]
	v_mfma_f32_16x16x32_bf16 v[106:109], v[154:157], v[176:179], v[106:109]
	v_mfma_f32_16x16x32_bf16 v[94:97], v[140:143], v[184:187], v[94:97]
	v_mfma_f32_16x16x32_bf16 v[90:93], v[154:157], v[184:187], v[90:93]
	v_mfma_f32_16x16x32_bf16 v[78:81], v[140:143], v[192:195], v[78:81]
	v_mfma_f32_16x16x32_bf16 v[74:77], v[154:157], v[192:195], v[74:77]
	v_mfma_f32_16x16x32_bf16 v[126:129], v[150:153], v[172:175], v[126:129]
	v_mfma_f32_16x16x32_bf16 v[122:125], v[158:161], v[172:175], v[122:125]
	v_mfma_f32_16x16x32_bf16 v[110:113], v[150:153], v[180:183], v[110:113]
	v_mfma_f32_16x16x32_bf16 v[106:109], v[158:161], v[180:183], v[106:109]
	v_mfma_f32_16x16x32_bf16 v[94:97], v[150:153], v[188:191], v[94:97]
	v_mfma_f32_16x16x32_bf16 v[90:93], v[158:161], v[188:191], v[90:93]
	v_mfma_f32_16x16x32_bf16 v[78:81], v[150:153], v[198:201], v[78:81]
	v_mfma_f32_16x16x32_bf16 v[74:77], v[158:161], v[198:201], v[74:77]
	s_setprio 0
	s_barrier
	s_add_i32 s52, 0, 0x1c000
	s_add_i32 s53, s83, s33
	v_add_u32_e32 v134, s52, v145
	v_lshl_add_u64 v[218:219], v[218:219], 0, s[10:11]
	s_mov_b32 m0, s53
	ds_read_b128 v[202:205], v134
	ds_read_b128 v[206:209], v134 offset:1024
	ds_read_b128 v[210:213], v134 offset:2048
	ds_read_b128 v[214:217], v134 offset:3072
	global_load_lds_dwordx4 v[218:219], off
	v_lshl_add_u64 v[218:219], v[220:221], 0, s[10:11]
	s_add_i32 m0, s53, 0x2000
	s_nop 0
	global_load_lds_dwordx4 v[218:219], off
	s_barrier
	s_waitcnt lgkmcnt(0)
	s_setprio 1
	s_waitcnt lgkmcnt(0)
	v_mfma_f32_16x16x32_bf16 v[118:121], v[202:205], v[168:171], v[118:121]
	v_mfma_f32_16x16x32_bf16 v[114:117], v[210:213], v[168:171], v[114:117]
	v_mfma_f32_16x16x32_bf16 v[102:105], v[202:205], v[176:179], v[102:105]
	v_mfma_f32_16x16x32_bf16 v[98:101], v[210:213], v[176:179], v[98:101]
	v_mfma_f32_16x16x32_bf16 v[86:89], v[202:205], v[184:187], v[86:89]
	v_mfma_f32_16x16x32_bf16 v[82:85], v[210:213], v[184:187], v[82:85]
	v_mfma_f32_16x16x32_bf16 v[70:73], v[202:205], v[192:195], v[70:73]
	v_mfma_f32_16x16x32_bf16 v[66:69], v[210:213], v[192:195], v[66:69]
	v_mfma_f32_16x16x32_bf16 v[118:121], v[206:209], v[172:175], v[118:121]
	v_mfma_f32_16x16x32_bf16 v[114:117], v[214:217], v[172:175], v[114:117]
	v_mfma_f32_16x16x32_bf16 v[102:105], v[206:209], v[180:183], v[102:105]
	v_mfma_f32_16x16x32_bf16 v[98:101], v[214:217], v[180:183], v[98:101]
	v_mfma_f32_16x16x32_bf16 v[86:89], v[206:209], v[188:191], v[86:89]
	v_mfma_f32_16x16x32_bf16 v[82:85], v[214:217], v[188:191], v[82:85]
	v_mfma_f32_16x16x32_bf16 v[70:73], v[206:209], v[198:201], v[70:73]
	v_mfma_f32_16x16x32_bf16 v[66:69], v[214:217], v[198:201], v[66:69]
	s_setprio 0
	s_mov_b32 m0, s59
	v_lshl_add_u64 v[218:219], v[222:223], 0, s[10:11]
	s_barrier
	ds_read_b128 v[168:171], v147 offset:49152
	ds_read_b128 v[172:175], v147 offset:50176
	ds_read_b128 v[176:179], v147 offset:51200
	ds_read_b128 v[180:183], v147 offset:52224
	ds_read_b128 v[184:187], v147 offset:53248
	ds_read_b128 v[188:191], v147 offset:54272
	ds_read_b128 v[192:195], v147 offset:55296
	ds_read_b128 v[198:201], v147 offset:56320
	global_load_lds_dwordx4 v[218:219], off
	v_lshl_add_u64 v[218:219], v[224:225], 0, s[10:11]
	s_mov_b32 m0, s62
	s_nop 0
	global_load_lds_dwordx4 v[218:219], off
	s_barrier
; DI unsigned pk_bf16(float a, float b) { f32x2 v = {a, b}; bf2_t r = __builtin_convertvector(v, bf2_t); return __builtin_bit_cast(unsigned, r); }
; DI float bflo(unsigned u) { return __uint_as_float(u << 16); }
; DI float bfhi(unsigned u) { return __uint_as_float(u & 0xffff0000u); }
; #define PG8_STAGE(bufoff, gbase, voff) do { _Pragma("unroll") for (int _i = 0; _i < 2; ++_i) \
;         __builtin_amdgcn_global_load_lds((const unsigned*)((const char*)(gbase) + (voff)[_i]), (LAS unsigned*)(lds + (bufoff) + ldsw + _i * 8192), 16, 0, 0); } while (0)
; #define PG8_LDA(dst, b, h) do { _Pragma("unroll") for (int m = 0; m < 4; ++m) _Pragma("unroll") for (int k = 0; k < 2; ++k) dst[m][k] = *(const LAS bf16x8*)(lds + PG8_SA(b, h) + aoff + m * 2048 + k * 1024); } while (0)
; #define PG8_WAIT_V(n) asm volatile("s_waitcnt vmcnt(" #n ")" ::: "memory")
; #define PG8_WAIT_L(n) asm volatile("s_waitcnt lgkmcnt(" #n ")" ::: "memory")
; #define PG8_BAR __builtin_amdgcn_s_barrier()
;     DI void operator()(const f32x4 (&acc)[2][2][4][2], const Unit& u, int wr, int wc, int fr, int fq) const {
;         const int row0 = u.pm * BM + wr * 64 + fr, col0 = u.pn * BM + wc * 32 + 4 * fq;
; #pragma unroll
;         for (int ai = 0; ai < 2; ++ai)
; #pragma unroll
;             for (int m = 0; m < 4; ++m) { const size_t o = (size_t)(row0 + ai * HALF + m * 16) * 1024 + col0;
; #pragma unroll
;                 for (int bj = 0; bj < 2; ++bj)
; #pragma unroll
;                     for (int n = 0; n < 2; ++n) { const size_t oo = o + bj * HALF + n * 16; f32x4 rv;
;                         if (RES_BF16) { const u32x2 t = *(const u32x2*)((const bf16_t*)res + oo); rv = (f32x4){bflo(t.x), bfhi(t.x), bflo(t.y), bfhi(t.y)}; }
;                         else rv = *(const f32x4*)((const float*)res + oo);
;                         const f32x4 v = acc[ai][bj][m][n] + rv; u32x2 w; w.x = pk_bf16(v.x, v.y); w.y = pk_bf16(v.z, v.w);
;                         *(u32x2*)(O + oo) = w; } }
; template <class Epi, class Sched>
; DI void gemm_phase(LAS unsigned char* lds, const Gemm g, const Sched& S, const Epi& E) {
;     ...
;             PG8_LDA(At, 1, 1); PG8_STAGE(PG8_SA(1, 0), a3, voffA);
;             PG8_BAR; PG8_WAIT_L(0); PG8_MMA(1, 0, At, B0); PG8_BAR; PG8_SCHED;
;             PG8_STAGE(PG8_SB(1, 1), b3 + hstep, voffB);
;             PG8_WAIT_V(6); PG8_BAR; PG8_MMA(1, 1, At, B1); PG8_BAR;
	s_waitcnt lgkmcnt(0)
	s_setprio 1
	s_waitcnt lgkmcnt(0)
	v_mfma_f32_16x16x32_bf16 v[62:65], v[140:143], v[168:171], v[62:65]
	v_mfma_f32_16x16x32_bf16 v[58:61], v[154:157], v[168:171], v[58:61]
	v_mfma_f32_16x16x32_bf16 v[46:49], v[140:143], v[176:179], v[46:49]
	v_mfma_f32_16x16x32_bf16 v[42:45], v[154:157], v[176:179], v[42:45]
	v_mfma_f32_16x16x32_bf16 v[30:33], v[140:143], v[184:187], v[30:33]
	v_mfma_f32_16x16x32_bf16 v[26:29], v[154:157], v[184:187], v[26:29]
	v_mfma_f32_16x16x32_bf16 v[14:17], v[140:143], v[192:195], v[14:17]
	v_mfma_f32_16x16x32_bf16 v[10:13], v[154:157], v[192:195], v[10:13]
	v_mfma_f32_16x16x32_bf16 v[62:65], v[150:153], v[172:175], v[62:65]
	v_mfma_f32_16x16x32_bf16 v[58:61], v[158:161], v[172:175], v[58:61]
	v_mfma_f32_16x16x32_bf16 v[46:49], v[150:153], v[180:183], v[46:49]
	v_mfma_f32_16x16x32_bf16 v[42:45], v[158:161], v[180:183], v[42:45]
	v_mfma_f32_16x16x32_bf16 v[30:33], v[150:153], v[188:191], v[30:33]
	v_mfma_f32_16x16x32_bf16 v[26:29], v[158:161], v[188:191], v[26:29]
	v_mfma_f32_16x16x32_bf16 v[14:17], v[150:153], v[198:201], v[14:17]
	v_mfma_f32_16x16x32_bf16 v[10:13], v[158:161], v[198:201], v[10:13]
	s_setprio 0
	s_barrier
	s_add_u32 s50, s50, 0x80080
	s_addc_u32 s51, s51, 0
	s_add_i32 s52, s52, s33
	v_lshl_add_u64 v[140:141], s[50:51], 0, v[132:133]
	s_mov_b32 m0, s52
	s_nop 0
	global_load_lds_dwordx4 v[140:141], off
	v_lshl_add_u64 v[140:141], s[50:51], 0, v[130:131]
	s_add_i32 m0, s52, 0x2000
	s_nop 0
	global_load_lds_dwordx4 v[140:141], off
	s_waitcnt vmcnt(6)
	s_barrier
	s_setprio 1
	v_mfma_f32_16x16x32_bf16 v[54:57], v[202:205], v[168:171], v[54:57]
	v_mfma_f32_16x16x32_bf16 v[50:53], v[210:213], v[168:171], v[50:53]
	v_mfma_f32_16x16x32_bf16 v[38:41], v[202:205], v[176:179], v[38:41]
	v_mfma_f32_16x16x32_bf16 v[34:37], v[210:213], v[176:179], v[34:37]
	v_mfma_f32_16x16x32_bf16 v[22:25], v[202:205], v[184:187], v[22:25]
	v_mfma_f32_16x16x32_bf16 v[18:21], v[210:213], v[184:187], v[18:21]
	v_mfma_f32_16x16x32_bf16 v[6:9], v[202:205], v[192:195], v[6:9]
	v_mfma_f32_16x16x32_bf16 v[2:5], v[210:213], v[192:195], v[2:5]
	v_mfma_f32_16x16x32_bf16 v[54:57], v[206:209], v[172:175], v[54:57]
	v_mfma_f32_16x16x32_bf16 v[50:53], v[214:217], v[172:175], v[50:53]
	v_mfma_f32_16x16x32_bf16 v[38:41], v[206:209], v[180:183], v[38:41]
	v_mfma_f32_16x16x32_bf16 v[34:37], v[214:217], v[180:183], v[34:37]
	v_mfma_f32_16x16x32_bf16 v[22:25], v[206:209], v[188:191], v[22:25]
	v_mfma_f32_16x16x32_bf16 v[18:21], v[214:217], v[188:191], v[18:21]
	v_mfma_f32_16x16x32_bf16 v[6:9], v[206:209], v[198:201], v[6:9]
	v_mfma_f32_16x16x32_bf16 v[2:5], v[214:217], v[198:201], v[2:5]
	s_setprio 0
	s_add_i32 s73, s73, 2
	s_add_u32 s42, s42, 0x100
	s_addc_u32 s43, s43, 0
	s_add_u32 s71, s71, 0x100
	s_addc_u32 s72, s72, 0
	s_cmp_gt_u32 s73, 29
	s_barrier
	s_cbranch_scc0 .LBB0_1523
	v_lshl_add_u32 v236, s56, 8, v144
	v_lshl_or_b32 v237, s84, 9, v149
	v_lshl_or_b32 v236, v236, 11, v237
	v_mov_b32_e32 v228, v236
	v_add_u32_e32 v229, 0x8000, v236
	v_add_u32_e32 v230, 0x10000, v236
	v_add_u32_e32 v231, 0x18000, v236
	v_add_u32_e32 v232, 0x40000, v236
	v_add_u32_e32 v233, 0x48000, v236
	v_add_u32_e32 v234, 0x50000, v236
	v_add_u32_e32 v235, 0x58000, v236
	v_and_b32_e32 v248, 63, v1
	v_lshrrev_b32_e32 v249, 3, v248
	v_and_b32_e32 v250, 3, v248
	v_lshl_or_b32 v250, v250, 4, v249
	v_lshlrev_b32_e32 v244, 2, v250
	v_add_u32_e32 v245, 32, v244
	v_and_b32_e32 v250, 0xffffffc0, v144
	v_add_u32_e32 v250, v250, v249
	v_lshl_add_u32 v250, s56, 8, v250
	v_mul_u32_u24_e32 v250, 0x800, v250
	v_and_b32_e32 v247, 0xffffffc0, v149
	v_lshl_or_b32 v247, s84, 9, v247
	v_and_b32_e32 v248, 7, v248
	v_lshl_add_u32 v247, v248, 3, v247
	v_add_u32_e32 v246, v250, v247
	s_mov_b32 s98, 0xf0f0f0f0
	s_mov_b32 s99, 0xf0f0f0f0
	global_load_dwordx2 v[140:141], v228, s[48:49] nt
	global_load_dwordx2 v[142:143], v228, s[48:49] offset:32 nt
	global_load_dwordx2 v[150:151], v228, s[48:49] offset:256 nt
	global_load_dwordx2 v[152:153], v228, s[48:49] offset:288 nt
	global_load_dwordx2 v[154:155], v229, s[48:49] nt
	global_load_dwordx2 v[156:157], v229, s[48:49] offset:32 nt
	global_load_dwordx2 v[158:159], v229, s[48:49] offset:256 nt
	global_load_dwordx2 v[160:161], v229, s[48:49] offset:288 nt
	global_load_dwordx2 v[168:169], v230, s[48:49] nt
	global_load_dwordx2 v[170:171], v230, s[48:49] offset:32 nt
	global_load_dwordx2 v[172:173], v230, s[48:49] offset:256 nt
	global_load_dwordx2 v[174:175], v230, s[48:49] offset:288 nt
	global_load_dwordx2 v[176:177], v231, s[48:49] nt
	global_load_dwordx2 v[178:179], v231, s[48:49] offset:32 nt
	global_load_dwordx2 v[180:181], v231, s[48:49] offset:256 nt
	global_load_dwordx2 v[182:183], v231, s[48:49] offset:288 nt
	global_load_dwordx2 v[184:185], v232, s[48:49] nt
	global_load_dwordx2 v[186:187], v232, s[48:49] offset:32 nt
	global_load_dwordx2 v[188:189], v232, s[48:49] offset:256 nt
	global_load_dwordx2 v[190:191], v232, s[48:49] offset:288 nt
	global_load_dwordx2 v[192:193], v233, s[48:49] nt
	global_load_dwordx2 v[194:195], v233, s[48:49] offset:32 nt
	global_load_dwordx2 v[198:199], v233, s[48:49] offset:256 nt
	global_load_dwordx2 v[200:201], v233, s[48:49] offset:288 nt
	global_load_dwordx2 v[202:203], v234, s[48:49] nt
	global_load_dwordx2 v[204:205], v234, s[48:49] offset:32 nt
	global_load_dwordx2 v[206:207], v234, s[48:49] offset:256 nt
	global_load_dwordx2 v[208:209], v234, s[48:49] offset:288 nt
	global_load_dwordx2 v[210:211], v235, s[48:49] nt
	global_load_dwordx2 v[212:213], v235, s[48:49] offset:32 nt
	global_load_dwordx2 v[214:215], v235, s[48:49] offset:256 nt
	global_load_dwordx2 v[216:217], v235, s[48:49] offset:288 nt
	s_waitcnt vmcnt(28)
; DI unsigned pk_bf16(float a, float b) { f32x2 v = {a, b}; bf2_t r = __builtin_convertvector(v, bf2_t); return __builtin_bit_cast(unsigned, r); }
; DI float bflo(unsigned u) { return __uint_as_float(u << 16); }
; DI float bfhi(unsigned u) { return __uint_as_float(u & 0xffff0000u); }
;     DI void operator()(const f32x4 (&acc)[2][2][4][2], const Unit& u, int wr, int wc, int fr, int fq) const {
;         const int row0 = u.pm * BM + wr * 64 + fr, col0 = u.pn * BM + wc * 32 + 4 * fq;
; #pragma unroll
;         for (int ai = 0; ai < 2; ++ai)
; #pragma unroll
;             for (int m = 0; m < 4; ++m) { const size_t o = (size_t)(row0 + ai * HALF + m * 16) * 1024 + col0;
; #pragma unroll
;                 for (int bj = 0; bj < 2; ++bj)
; #pragma unroll
;                     for (int n = 0; n < 2; ++n) { const size_t oo = o + bj * HALF + n * 16; f32x4 rv;
;                         if (RES_BF16) { const u32x2 t = *(const u32x2*)((const bf16_t*)res + oo); rv = (f32x4){bflo(t.x), bfhi(t.x), bflo(t.y), bfhi(t.y)}; }
;                         else rv = *(const f32x4*)((const float*)res + oo);
;                         const f32x4 v = acc[ai][bj][m][n] + rv; u32x2 w; w.x = pk_bf16(v.x, v.y); w.y = pk_bf16(v.z, v.w);
;                         *(u32x2*)(O + oo) = w; } }
	v_lshlrev_b32_e32 v226, 16, v141
	v_and_b32_e32 v227, 0xffff0000, v141
	v_and_b32_e32 v141, 0xffff0000, v140
	v_lshlrev_b32_e32 v140, 16, v140
	v_pk_add_f32 v[128:129], v[128:129], v[226:227]
	v_pk_add_f32 v[126:127], v[126:127], v[140:141]
	v_lshlrev_b32_e32 v240, 16, v143
	v_and_b32_e32 v241, 0xffff0000, v143
	v_and_b32_e32 v143, 0xffff0000, v142
	v_lshlrev_b32_e32 v142, 16, v142
	v_pk_add_f32 v[124:125], v[124:125], v[240:241]
	v_pk_add_f32 v[122:123], v[122:123], v[142:143]
	v_lshlrev_b32_e32 v226, 16, v151
	v_and_b32_e32 v227, 0xffff0000, v151
	v_and_b32_e32 v151, 0xffff0000, v150
	v_lshlrev_b32_e32 v150, 16, v150
	v_pk_add_f32 v[120:121], v[120:121], v[226:227]
	v_pk_add_f32 v[118:119], v[118:119], v[150:151]
	v_lshlrev_b32_e32 v240, 16, v153
	v_and_b32_e32 v241, 0xffff0000, v153
	v_and_b32_e32 v153, 0xffff0000, v152
	v_lshlrev_b32_e32 v152, 16, v152
	v_pk_add_f32 v[116:117], v[116:117], v[240:241]
	v_pk_add_f32 v[114:115], v[114:115], v[152:153]
	v_cvt_pk_bf16_f32 v126, v126, v127
	v_cvt_pk_bf16_f32 v127, v128, v129
	v_cvt_pk_bf16_f32 v122, v122, v123
	v_cvt_pk_bf16_f32 v123, v124, v125
	v_cvt_pk_bf16_f32 v118, v118, v119
	v_cvt_pk_bf16_f32 v119, v120, v121
	v_cvt_pk_bf16_f32 v114, v114, v115
	v_cvt_pk_bf16_f32 v115, v116, v117
	ds_bpermute_b32 v140, v244, v126
	ds_bpermute_b32 v141, v244, v127
	ds_bpermute_b32 v142, v244, v122
	ds_bpermute_b32 v143, v244, v123
	ds_bpermute_b32 v150, v245, v126
	ds_bpermute_b32 v151, v245, v127
	ds_bpermute_b32 v152, v245, v122
	ds_bpermute_b32 v153, v245, v123
	s_waitcnt lgkmcnt(0)
	v_cndmask_b32_e64 v140, v140, v142, s[98:99]
	v_cndmask_b32_e64 v141, v141, v143, s[98:99]
	v_mov_b32_e32 v142, v246
	global_store_dwordx2 v142, v[140:141], s[8:9]
	v_cndmask_b32_e64 v150, v150, v152, s[98:99]
	v_cndmask_b32_e64 v151, v151, v153, s[98:99]
	v_add_u32_e32 v152, 0x4000, v246
	global_store_dwordx2 v152, v[150:151], s[8:9]
	ds_bpermute_b32 v140, v244, v118
	ds_bpermute_b32 v141, v244, v119
	ds_bpermute_b32 v142, v244, v114
	ds_bpermute_b32 v143, v244, v115
	ds_bpermute_b32 v150, v245, v118
	ds_bpermute_b32 v151, v245, v119
	ds_bpermute_b32 v152, v245, v114
	ds_bpermute_b32 v153, v245, v115
	s_waitcnt lgkmcnt(0)
	v_cndmask_b32_e64 v140, v140, v142, s[98:99]
	v_cndmask_b32_e64 v141, v141, v143, s[98:99]
	v_mov_b32_e32 v142, v246
	global_store_dwordx2 v142, v[140:141], s[8:9] offset:256
	v_cndmask_b32_e64 v150, v150, v152, s[98:99]
	v_cndmask_b32_e64 v151, v151, v153, s[98:99]
	v_add_u32_e32 v152, 0x4000, v246
	global_store_dwordx2 v152, v[150:151], s[8:9] offset:256
	s_waitcnt vmcnt(28)
	v_lshlrev_b32_e32 v226, 16, v155
	v_and_b32_e32 v227, 0xffff0000, v155
	v_and_b32_e32 v155, 0xffff0000, v154
	v_lshlrev_b32_e32 v154, 16, v154
	v_pk_add_f32 v[112:113], v[112:113], v[226:227]
	v_pk_add_f32 v[110:111], v[110:111], v[154:155]
	v_lshlrev_b32_e32 v240, 16, v157
	v_and_b32_e32 v241, 0xffff0000, v157
	v_and_b32_e32 v157, 0xffff0000, v156
	v_lshlrev_b32_e32 v156, 16, v156
	v_pk_add_f32 v[108:109], v[108:109], v[240:241]
	v_pk_add_f32 v[106:107], v[106:107], v[156:157]
	v_lshlrev_b32_e32 v226, 16, v159
	v_and_b32_e32 v227, 0xffff0000, v159
	v_and_b32_e32 v159, 0xffff0000, v158
	v_lshlrev_b32_e32 v158, 16, v158
	v_pk_add_f32 v[104:105], v[104:105], v[226:227]
	v_pk_add_f32 v[102:103], v[102:103], v[158:159]
	v_lshlrev_b32_e32 v240, 16, v161
	v_and_b32_e32 v241, 0xffff0000, v161
	v_and_b32_e32 v161, 0xffff0000, v160
	v_lshlrev_b32_e32 v160, 16, v160
	v_pk_add_f32 v[100:101], v[100:101], v[240:241]
	v_pk_add_f32 v[98:99], v[98:99], v[160:161]
	v_cvt_pk_bf16_f32 v110, v110, v111
	v_cvt_pk_bf16_f32 v111, v112, v113
	v_cvt_pk_bf16_f32 v106, v106, v107
	v_cvt_pk_bf16_f32 v107, v108, v109
	v_cvt_pk_bf16_f32 v102, v102, v103
	v_cvt_pk_bf16_f32 v103, v104, v105
	v_cvt_pk_bf16_f32 v98, v98, v99
	v_cvt_pk_bf16_f32 v99, v100, v101
	ds_bpermute_b32 v154, v244, v110
	ds_bpermute_b32 v155, v244, v111
	ds_bpermute_b32 v156, v244, v106
	ds_bpermute_b32 v157, v244, v107
	ds_bpermute_b32 v158, v245, v110
	ds_bpermute_b32 v159, v245, v111
	ds_bpermute_b32 v160, v245, v106
	ds_bpermute_b32 v161, v245, v107
	s_waitcnt lgkmcnt(0)
	v_cndmask_b32_e64 v154, v154, v156, s[98:99]
	v_cndmask_b32_e64 v155, v155, v157, s[98:99]
	v_add_u32_e32 v156, 0x8000, v246
	global_store_dwordx2 v156, v[154:155], s[8:9]
	v_cndmask_b32_e64 v158, v158, v160, s[98:99]
	v_cndmask_b32_e64 v159, v159, v161, s[98:99]
	v_add_u32_e32 v160, 0xc000, v246
	global_store_dwordx2 v160, v[158:159], s[8:9]
	ds_bpermute_b32 v154, v244, v102
	ds_bpermute_b32 v155, v244, v103
	ds_bpermute_b32 v156, v244, v98
	ds_bpermute_b32 v157, v244, v99
	ds_bpermute_b32 v158, v245, v102
	ds_bpermute_b32 v159, v245, v103
	ds_bpermute_b32 v160, v245, v98
	ds_bpermute_b32 v161, v245, v99
	s_waitcnt lgkmcnt(0)
	v_cndmask_b32_e64 v154, v154, v156, s[98:99]
	v_cndmask_b32_e64 v155, v155, v157, s[98:99]
	v_add_u32_e32 v156, 0x8000, v246
	global_store_dwordx2 v156, v[154:155], s[8:9] offset:256
	v_cndmask_b32_e64 v158, v158, v160, s[98:99]
	v_cndmask_b32_e64 v159, v159, v161, s[98:99]
	v_add_u32_e32 v160, 0xc000, v246
	global_store_dwordx2 v160, v[158:159], s[8:9] offset:256
	s_waitcnt vmcnt(28)
; DI unsigned pk_bf16(float a, float b) { f32x2 v = {a, b}; bf2_t r = __builtin_convertvector(v, bf2_t); return __builtin_bit_cast(unsigned, r); }
; DI float bflo(unsigned u) { return __uint_as_float(u << 16); }
; DI float bfhi(unsigned u) { return __uint_as_float(u & 0xffff0000u); }
;     DI void operator()(const f32x4 (&acc)[2][2][4][2], const Unit& u, int wr, int wc, int fr, int fq) const {
;         const int row0 = u.pm * BM + wr * 64 + fr, col0 = u.pn * BM + wc * 32 + 4 * fq;
; #pragma unroll
;         for (int ai = 0; ai < 2; ++ai)
; #pragma unroll
;             for (int m = 0; m < 4; ++m) { const size_t o = (size_t)(row0 + ai * HALF + m * 16) * 1024 + col0;
; #pragma unroll
;                 for (int bj = 0; bj < 2; ++bj)
; #pragma unroll
;                     for (int n = 0; n < 2; ++n) { const size_t oo = o + bj * HALF + n * 16; f32x4 rv;
;                         if (RES_BF16) { const u32x2 t = *(const u32x2*)((const bf16_t*)res + oo); rv = (f32x4){bflo(t.x), bfhi(t.x), bflo(t.y), bfhi(t.y)}; }
;                         else rv = *(const f32x4*)((const float*)res + oo);
;                         const f32x4 v = acc[ai][bj][m][n] + rv; u32x2 w; w.x = pk_bf16(v.x, v.y); w.y = pk_bf16(v.z, v.w);
;                         *(u32x2*)(O + oo) = w; } }
	v_lshlrev_b32_e32 v226, 16, v169
	v_and_b32_e32 v227, 0xffff0000, v169
	v_and_b32_e32 v169, 0xffff0000, v168
	v_lshlrev_b32_e32 v168, 16, v168
	v_pk_add_f32 v[96:97], v[96:97], v[226:227]
	v_pk_add_f32 v[94:95], v[94:95], v[168:169]
	v_lshlrev_b32_e32 v240, 16, v171
	v_and_b32_e32 v241, 0xffff0000, v171
	v_and_b32_e32 v171, 0xffff0000, v170
	v_lshlrev_b32_e32 v170, 16, v170
	v_pk_add_f32 v[92:93], v[92:93], v[240:241]
	v_pk_add_f32 v[90:91], v[90:91], v[170:171]
	v_lshlrev_b32_e32 v226, 16, v173
	v_and_b32_e32 v227, 0xffff0000, v173
	v_and_b32_e32 v173, 0xffff0000, v172
	v_lshlrev_b32_e32 v172, 16, v172
	v_pk_add_f32 v[88:89], v[88:89], v[226:227]
	v_pk_add_f32 v[86:87], v[86:87], v[172:173]
	v_lshlrev_b32_e32 v240, 16, v175
	v_and_b32_e32 v241, 0xffff0000, v175
	v_and_b32_e32 v175, 0xffff0000, v174
	v_lshlrev_b32_e32 v174, 16, v174
	v_pk_add_f32 v[84:85], v[84:85], v[240:241]
	v_pk_add_f32 v[82:83], v[82:83], v[174:175]
	v_cvt_pk_bf16_f32 v94, v94, v95
	v_cvt_pk_bf16_f32 v95, v96, v97
	v_cvt_pk_bf16_f32 v90, v90, v91
	v_cvt_pk_bf16_f32 v91, v92, v93
	v_cvt_pk_bf16_f32 v86, v86, v87
	v_cvt_pk_bf16_f32 v87, v88, v89
	v_cvt_pk_bf16_f32 v82, v82, v83
	v_cvt_pk_bf16_f32 v83, v84, v85
	ds_bpermute_b32 v168, v244, v94
	ds_bpermute_b32 v169, v244, v95
	ds_bpermute_b32 v170, v244, v90
	ds_bpermute_b32 v171, v244, v91
	ds_bpermute_b32 v172, v245, v94
	ds_bpermute_b32 v173, v245, v95
	ds_bpermute_b32 v174, v245, v90
	ds_bpermute_b32 v175, v245, v91
	s_waitcnt lgkmcnt(0)
	v_cndmask_b32_e64 v168, v168, v170, s[98:99]
	v_cndmask_b32_e64 v169, v169, v171, s[98:99]
	v_add_u32_e32 v170, 0x10000, v246
	global_store_dwordx2 v170, v[168:169], s[8:9]
	v_cndmask_b32_e64 v172, v172, v174, s[98:99]
	v_cndmask_b32_e64 v173, v173, v175, s[98:99]
	v_add_u32_e32 v174, 0x14000, v246
	global_store_dwordx2 v174, v[172:173], s[8:9]
	ds_bpermute_b32 v168, v244, v86
	ds_bpermute_b32 v169, v244, v87
	ds_bpermute_b32 v170, v244, v82
	ds_bpermute_b32 v171, v244, v83
	ds_bpermute_b32 v172, v245, v86
	ds_bpermute_b32 v173, v245, v87
	ds_bpermute_b32 v174, v245, v82
	ds_bpermute_b32 v175, v245, v83
	s_waitcnt lgkmcnt(0)
	v_cndmask_b32_e64 v168, v168, v170, s[98:99]
	v_cndmask_b32_e64 v169, v169, v171, s[98:99]
	v_add_u32_e32 v170, 0x10000, v246
	global_store_dwordx2 v170, v[168:169], s[8:9] offset:256
	v_cndmask_b32_e64 v172, v172, v174, s[98:99]
	v_cndmask_b32_e64 v173, v173, v175, s[98:99]
	v_add_u32_e32 v174, 0x14000, v246
	global_store_dwordx2 v174, v[172:173], s[8:9] offset:256
	s_waitcnt vmcnt(28)
	v_lshlrev_b32_e32 v226, 16, v177
	v_and_b32_e32 v227, 0xffff0000, v177
	v_and_b32_e32 v177, 0xffff0000, v176
	v_lshlrev_b32_e32 v176, 16, v176
	v_pk_add_f32 v[80:81], v[80:81], v[226:227]
	v_pk_add_f32 v[78:79], v[78:79], v[176:177]
	v_lshlrev_b32_e32 v240, 16, v179
	v_and_b32_e32 v241, 0xffff0000, v179
	v_and_b32_e32 v179, 0xffff0000, v178
	v_lshlrev_b32_e32 v178, 16, v178
	v_pk_add_f32 v[76:77], v[76:77], v[240:241]
	v_pk_add_f32 v[74:75], v[74:75], v[178:179]
	v_lshlrev_b32_e32 v226, 16, v181
	v_and_b32_e32 v227, 0xffff0000, v181
	v_and_b32_e32 v181, 0xffff0000, v180
	v_lshlrev_b32_e32 v180, 16, v180
	v_pk_add_f32 v[72:73], v[72:73], v[226:227]
	v_pk_add_f32 v[70:71], v[70:71], v[180:181]
	v_lshlrev_b32_e32 v240, 16, v183
	v_and_b32_e32 v241, 0xffff0000, v183
	v_and_b32_e32 v183, 0xffff0000, v182
	v_lshlrev_b32_e32 v182, 16, v182
	v_pk_add_f32 v[68:69], v[68:69], v[240:241]
	v_pk_add_f32 v[66:67], v[66:67], v[182:183]
	v_cvt_pk_bf16_f32 v78, v78, v79
	v_cvt_pk_bf16_f32 v79, v80, v81
	v_cvt_pk_bf16_f32 v74, v74, v75
	v_cvt_pk_bf16_f32 v75, v76, v77
	v_cvt_pk_bf16_f32 v70, v70, v71
	v_cvt_pk_bf16_f32 v71, v72, v73
	v_cvt_pk_bf16_f32 v66, v66, v67
	v_cvt_pk_bf16_f32 v67, v68, v69
	ds_bpermute_b32 v176, v244, v78
	ds_bpermute_b32 v177, v244, v79
	ds_bpermute_b32 v178, v244, v74
	ds_bpermute_b32 v179, v244, v75
	ds_bpermute_b32 v180, v245, v78
	ds_bpermute_b32 v181, v245, v79
	ds_bpermute_b32 v182, v245, v74
	ds_bpermute_b32 v183, v245, v75
	s_waitcnt lgkmcnt(0)
	v_cndmask_b32_e64 v176, v176, v178, s[98:99]
	v_cndmask_b32_e64 v177, v177, v179, s[98:99]
	v_add_u32_e32 v178, 0x18000, v246
	global_store_dwordx2 v178, v[176:177], s[8:9]
	v_cndmask_b32_e64 v180, v180, v182, s[98:99]
	v_cndmask_b32_e64 v181, v181, v183, s[98:99]
	v_add_u32_e32 v182, 0x1c000, v246
	global_store_dwordx2 v182, v[180:181], s[8:9]
	ds_bpermute_b32 v176, v244, v70
	ds_bpermute_b32 v177, v244, v71
	ds_bpermute_b32 v178, v244, v66
	ds_bpermute_b32 v179, v244, v67
	ds_bpermute_b32 v180, v245, v70
	ds_bpermute_b32 v181, v245, v71
	ds_bpermute_b32 v182, v245, v66
	ds_bpermute_b32 v183, v245, v67
	s_waitcnt lgkmcnt(0)
	v_cndmask_b32_e64 v176, v176, v178, s[98:99]
	v_cndmask_b32_e64 v177, v177, v179, s[98:99]
	v_add_u32_e32 v178, 0x18000, v246
	global_store_dwordx2 v178, v[176:177], s[8:9] offset:256
	v_cndmask_b32_e64 v180, v180, v182, s[98:99]
	v_cndmask_b32_e64 v181, v181, v183, s[98:99]
	v_add_u32_e32 v182, 0x1c000, v246
	global_store_dwordx2 v182, v[180:181], s[8:9] offset:256
	s_waitcnt vmcnt(28)
; DI unsigned pk_bf16(float a, float b) { f32x2 v = {a, b}; bf2_t r = __builtin_convertvector(v, bf2_t); return __builtin_bit_cast(unsigned, r); }
; DI float bflo(unsigned u) { return __uint_as_float(u << 16); }
; DI float bfhi(unsigned u) { return __uint_as_float(u & 0xffff0000u); }
;     DI void operator()(const f32x4 (&acc)[2][2][4][2], const Unit& u, int wr, int wc, int fr, int fq) const {
;     ...
;             for (int m = 0; m < 4; ++m) { const size_t o = (size_t)(row0 + ai * HALF + m * 16) * 1024 + col0;
; #pragma unroll
;                 for (int bj = 0; bj < 2; ++bj)
; #pragma unroll
;                     for (int n = 0; n < 2; ++n) { const size_t oo = o + bj * HALF + n * 16; f32x4 rv;
;                         if (RES_BF16) { const u32x2 t = *(const u32x2*)((const bf16_t*)res + oo); rv = (f32x4){bflo(t.x), bfhi(t.x), bflo(t.y), bfhi(t.y)}; }
;                         else rv = *(const f32x4*)((const float*)res + oo);
;                         const f32x4 v = acc[ai][bj][m][n] + rv; u32x2 w; w.x = pk_bf16(v.x, v.y); w.y = pk_bf16(v.z, v.w);
;                         *(u32x2*)(O + oo) = w; } }
	v_lshlrev_b32_e32 v226, 16, v185
	v_and_b32_e32 v227, 0xffff0000, v185
	v_and_b32_e32 v185, 0xffff0000, v184
	v_lshlrev_b32_e32 v184, 16, v184
	v_pk_add_f32 v[64:65], v[64:65], v[226:227]
	v_pk_add_f32 v[62:63], v[62:63], v[184:185]
	v_lshlrev_b32_e32 v240, 16, v187
	v_and_b32_e32 v241, 0xffff0000, v187
	v_and_b32_e32 v187, 0xffff0000, v186
	v_lshlrev_b32_e32 v186, 16, v186
	v_pk_add_f32 v[60:61], v[60:61], v[240:241]
	v_pk_add_f32 v[58:59], v[58:59], v[186:187]
	v_lshlrev_b32_e32 v226, 16, v189
	v_and_b32_e32 v227, 0xffff0000, v189
	v_and_b32_e32 v189, 0xffff0000, v188
	v_lshlrev_b32_e32 v188, 16, v188
	v_pk_add_f32 v[56:57], v[56:57], v[226:227]
	v_pk_add_f32 v[54:55], v[54:55], v[188:189]
	v_lshlrev_b32_e32 v240, 16, v191
	v_and_b32_e32 v241, 0xffff0000, v191
	v_and_b32_e32 v191, 0xffff0000, v190
	v_lshlrev_b32_e32 v190, 16, v190
	v_pk_add_f32 v[52:53], v[52:53], v[240:241]
	v_pk_add_f32 v[50:51], v[50:51], v[190:191]
	v_cvt_pk_bf16_f32 v62, v62, v63
	v_cvt_pk_bf16_f32 v63, v64, v65
	v_cvt_pk_bf16_f32 v58, v58, v59
	v_cvt_pk_bf16_f32 v59, v60, v61
	v_cvt_pk_bf16_f32 v54, v54, v55
	v_cvt_pk_bf16_f32 v55, v56, v57
	v_cvt_pk_bf16_f32 v50, v50, v51
	v_cvt_pk_bf16_f32 v51, v52, v53
	ds_bpermute_b32 v184, v244, v62
	ds_bpermute_b32 v185, v244, v63
	ds_bpermute_b32 v186, v244, v58
	ds_bpermute_b32 v187, v244, v59
	ds_bpermute_b32 v188, v245, v62
	ds_bpermute_b32 v189, v245, v63
	ds_bpermute_b32 v190, v245, v58
	ds_bpermute_b32 v191, v245, v59
	s_waitcnt lgkmcnt(0)
	v_cndmask_b32_e64 v184, v184, v186, s[98:99]
	v_cndmask_b32_e64 v185, v185, v187, s[98:99]
	v_add_u32_e32 v186, 0x40000, v246
	global_store_dwordx2 v186, v[184:185], s[8:9]
	v_cndmask_b32_e64 v188, v188, v190, s[98:99]
	v_cndmask_b32_e64 v189, v189, v191, s[98:99]
	v_add_u32_e32 v190, 0x44000, v246
	global_store_dwordx2 v190, v[188:189], s[8:9]
	ds_bpermute_b32 v184, v244, v54
	ds_bpermute_b32 v185, v244, v55
	ds_bpermute_b32 v186, v244, v50
	ds_bpermute_b32 v187, v244, v51
	ds_bpermute_b32 v188, v245, v54
	ds_bpermute_b32 v189, v245, v55
	ds_bpermute_b32 v190, v245, v50
	ds_bpermute_b32 v191, v245, v51
	s_waitcnt lgkmcnt(0)
	v_cndmask_b32_e64 v184, v184, v186, s[98:99]
	v_cndmask_b32_e64 v185, v185, v187, s[98:99]
	v_add_u32_e32 v186, 0x40000, v246
	global_store_dwordx2 v186, v[184:185], s[8:9] offset:256
	v_cndmask_b32_e64 v188, v188, v190, s[98:99]
	v_cndmask_b32_e64 v189, v189, v191, s[98:99]
	v_add_u32_e32 v190, 0x44000, v246
	global_store_dwordx2 v190, v[188:189], s[8:9] offset:256
	s_waitcnt vmcnt(28)
	v_lshlrev_b32_e32 v226, 16, v193
	v_and_b32_e32 v227, 0xffff0000, v193
	v_and_b32_e32 v193, 0xffff0000, v192
	v_lshlrev_b32_e32 v192, 16, v192
	v_pk_add_f32 v[48:49], v[48:49], v[226:227]
	v_pk_add_f32 v[46:47], v[46:47], v[192:193]
	v_lshlrev_b32_e32 v240, 16, v195
	v_and_b32_e32 v241, 0xffff0000, v195
	v_and_b32_e32 v195, 0xffff0000, v194
	v_lshlrev_b32_e32 v194, 16, v194
	v_pk_add_f32 v[44:45], v[44:45], v[240:241]
	v_pk_add_f32 v[42:43], v[42:43], v[194:195]
	v_lshlrev_b32_e32 v226, 16, v199
	v_and_b32_e32 v227, 0xffff0000, v199
	v_and_b32_e32 v199, 0xffff0000, v198
	v_lshlrev_b32_e32 v198, 16, v198
	v_pk_add_f32 v[40:41], v[40:41], v[226:227]
	v_pk_add_f32 v[38:39], v[38:39], v[198:199]
	v_lshlrev_b32_e32 v240, 16, v201
	v_and_b32_e32 v241, 0xffff0000, v201
	v_and_b32_e32 v201, 0xffff0000, v200
	v_lshlrev_b32_e32 v200, 16, v200
	v_pk_add_f32 v[36:37], v[36:37], v[240:241]
	v_pk_add_f32 v[34:35], v[34:35], v[200:201]
	v_cvt_pk_bf16_f32 v46, v46, v47
	v_cvt_pk_bf16_f32 v47, v48, v49
	v_cvt_pk_bf16_f32 v42, v42, v43
	v_cvt_pk_bf16_f32 v43, v44, v45
	v_cvt_pk_bf16_f32 v38, v38, v39
	v_cvt_pk_bf16_f32 v39, v40, v41
	v_cvt_pk_bf16_f32 v34, v34, v35
	v_cvt_pk_bf16_f32 v35, v36, v37
	ds_bpermute_b32 v192, v244, v46
	ds_bpermute_b32 v193, v244, v47
	ds_bpermute_b32 v194, v244, v42
	ds_bpermute_b32 v195, v244, v43
	ds_bpermute_b32 v198, v245, v46
	ds_bpermute_b32 v199, v245, v47
	ds_bpermute_b32 v200, v245, v42
	ds_bpermute_b32 v201, v245, v43
	s_waitcnt lgkmcnt(0)
	v_cndmask_b32_e64 v192, v192, v194, s[98:99]
	v_cndmask_b32_e64 v193, v193, v195, s[98:99]
	v_add_u32_e32 v194, 0x48000, v246
	global_store_dwordx2 v194, v[192:193], s[8:9]
	v_cndmask_b32_e64 v198, v198, v200, s[98:99]
	v_cndmask_b32_e64 v199, v199, v201, s[98:99]
	v_add_u32_e32 v200, 0x4c000, v246
	global_store_dwordx2 v200, v[198:199], s[8:9]
	ds_bpermute_b32 v192, v244, v38
	ds_bpermute_b32 v193, v244, v39
	ds_bpermute_b32 v194, v244, v34
	ds_bpermute_b32 v195, v244, v35
	ds_bpermute_b32 v198, v245, v38
	ds_bpermute_b32 v199, v245, v39
	ds_bpermute_b32 v200, v245, v34
	ds_bpermute_b32 v201, v245, v35
	s_waitcnt lgkmcnt(0)
	v_cndmask_b32_e64 v192, v192, v194, s[98:99]
	v_cndmask_b32_e64 v193, v193, v195, s[98:99]
	v_add_u32_e32 v194, 0x48000, v246
	global_store_dwordx2 v194, v[192:193], s[8:9] offset:256
	v_cndmask_b32_e64 v198, v198, v200, s[98:99]
	v_cndmask_b32_e64 v199, v199, v201, s[98:99]
	v_add_u32_e32 v200, 0x4c000, v246
	global_store_dwordx2 v200, v[198:199], s[8:9] offset:256
	s_waitcnt vmcnt(28)
; DI unsigned pk_bf16(float a, float b) { f32x2 v = {a, b}; bf2_t r = __builtin_convertvector(v, bf2_t); return __builtin_bit_cast(unsigned, r); }
; DI float bflo(unsigned u) { return __uint_as_float(u << 16); }
; DI float bfhi(unsigned u) { return __uint_as_float(u & 0xffff0000u); }
; #define PG8_WAIT_V(n) asm volatile("s_waitcnt vmcnt(" #n ")" ::: "memory")
; #define PG8_BAR __builtin_amdgcn_s_barrier()
;     DI void operator()(const f32x4 (&acc)[2][2][4][2], const Unit& u, int wr, int wc, int fr, int fq) const {
;     ...
;             for (int m = 0; m < 4; ++m) { const size_t o = (size_t)(row0 + ai * HALF + m * 16) * 1024 + col0;
; #pragma unroll
;                 for (int bj = 0; bj < 2; ++bj)
; #pragma unroll
;                     for (int n = 0; n < 2; ++n) { const size_t oo = o + bj * HALF + n * 16; f32x4 rv;
;                         if (RES_BF16) { const u32x2 t = *(const u32x2*)((const bf16_t*)res + oo); rv = (f32x4){bflo(t.x), bfhi(t.x), bflo(t.y), bfhi(t.y)}; }
;                         else rv = *(const f32x4*)((const float*)res + oo);
;                         const f32x4 v = acc[ai][bj][m][n] + rv; u32x2 w; w.x = pk_bf16(v.x, v.y); w.y = pk_bf16(v.z, v.w);
;                         *(u32x2*)(O + oo) = w; } }
; template <class Epi, class Sched>
; DI void gemm_phase(LAS unsigned char* lds, const Gemm g, const Sched& S, const Epi& E) {
;     ...
;         E(acc, cur, wr, wc, fr, fq);
;         if (!has_next) break;
; #pragma unroll
;         for (int a = 0; a < 2; ++a)
; #pragma unroll
;             for (int b = 0; b < 2; ++b)
; #pragma unroll
;                 for (int m = 0; m < 4; ++m)
; #pragma unroll
;                     for (int n = 0; n < 2; ++n) acc[a][b][m][n] = (f32x4){0.f, 0.f, 0.f, 0.f};
;         cur = nxt; cA = nA; cB = nB; ++ui;
;     }
;     PG8_WAIT_V(0);
;     if (wr == 0) PG8_BAR;
;     PG8_BAR;
	v_lshlrev_b32_e32 v226, 16, v203
	v_and_b32_e32 v227, 0xffff0000, v203
	v_and_b32_e32 v203, 0xffff0000, v202
	v_lshlrev_b32_e32 v202, 16, v202
	v_pk_add_f32 v[32:33], v[32:33], v[226:227]
	v_pk_add_f32 v[30:31], v[30:31], v[202:203]
	v_lshlrev_b32_e32 v240, 16, v205
	v_and_b32_e32 v241, 0xffff0000, v205
	v_and_b32_e32 v205, 0xffff0000, v204
	v_lshlrev_b32_e32 v204, 16, v204
	v_pk_add_f32 v[28:29], v[28:29], v[240:241]
	v_pk_add_f32 v[26:27], v[26:27], v[204:205]
	v_lshlrev_b32_e32 v226, 16, v207
	v_and_b32_e32 v227, 0xffff0000, v207
	v_and_b32_e32 v207, 0xffff0000, v206
	v_lshlrev_b32_e32 v206, 16, v206
	v_pk_add_f32 v[24:25], v[24:25], v[226:227]
	v_pk_add_f32 v[22:23], v[22:23], v[206:207]
	v_lshlrev_b32_e32 v240, 16, v209
	v_and_b32_e32 v241, 0xffff0000, v209
	v_and_b32_e32 v209, 0xffff0000, v208
	v_lshlrev_b32_e32 v208, 16, v208
	v_pk_add_f32 v[20:21], v[20:21], v[240:241]
	v_pk_add_f32 v[18:19], v[18:19], v[208:209]
	v_cvt_pk_bf16_f32 v30, v30, v31
	v_cvt_pk_bf16_f32 v31, v32, v33
	v_cvt_pk_bf16_f32 v26, v26, v27
	v_cvt_pk_bf16_f32 v27, v28, v29
	v_cvt_pk_bf16_f32 v22, v22, v23
	v_cvt_pk_bf16_f32 v23, v24, v25
	v_cvt_pk_bf16_f32 v18, v18, v19
	v_cvt_pk_bf16_f32 v19, v20, v21
	ds_bpermute_b32 v202, v244, v30
	ds_bpermute_b32 v203, v244, v31
	ds_bpermute_b32 v204, v244, v26
	ds_bpermute_b32 v205, v244, v27
	ds_bpermute_b32 v206, v245, v30
	ds_bpermute_b32 v207, v245, v31
	ds_bpermute_b32 v208, v245, v26
	ds_bpermute_b32 v209, v245, v27
	s_waitcnt lgkmcnt(0)
	v_cndmask_b32_e64 v202, v202, v204, s[98:99]
	v_cndmask_b32_e64 v203, v203, v205, s[98:99]
	v_add_u32_e32 v204, 0x50000, v246
	global_store_dwordx2 v204, v[202:203], s[8:9]
	v_cndmask_b32_e64 v206, v206, v208, s[98:99]
	v_cndmask_b32_e64 v207, v207, v209, s[98:99]
	v_add_u32_e32 v208, 0x54000, v246
	global_store_dwordx2 v208, v[206:207], s[8:9]
	ds_bpermute_b32 v202, v244, v22
	ds_bpermute_b32 v203, v244, v23
	ds_bpermute_b32 v204, v244, v18
	ds_bpermute_b32 v205, v244, v19
	ds_bpermute_b32 v206, v245, v22
	ds_bpermute_b32 v207, v245, v23
	ds_bpermute_b32 v208, v245, v18
	ds_bpermute_b32 v209, v245, v19
	s_waitcnt lgkmcnt(0)
	v_cndmask_b32_e64 v202, v202, v204, s[98:99]
	v_cndmask_b32_e64 v203, v203, v205, s[98:99]
	v_add_u32_e32 v204, 0x50000, v246
	global_store_dwordx2 v204, v[202:203], s[8:9] offset:256
	v_cndmask_b32_e64 v206, v206, v208, s[98:99]
	v_cndmask_b32_e64 v207, v207, v209, s[98:99]
	v_add_u32_e32 v208, 0x54000, v246
	global_store_dwordx2 v208, v[206:207], s[8:9] offset:256
	s_waitcnt vmcnt(28)
	v_lshlrev_b32_e32 v226, 16, v211
	v_and_b32_e32 v227, 0xffff0000, v211
	v_and_b32_e32 v211, 0xffff0000, v210
	v_lshlrev_b32_e32 v210, 16, v210
	v_pk_add_f32 v[16:17], v[16:17], v[226:227]
	v_pk_add_f32 v[14:15], v[14:15], v[210:211]
	v_lshlrev_b32_e32 v240, 16, v213
	v_and_b32_e32 v241, 0xffff0000, v213
	v_and_b32_e32 v213, 0xffff0000, v212
	v_lshlrev_b32_e32 v212, 16, v212
	v_pk_add_f32 v[12:13], v[12:13], v[240:241]
	v_pk_add_f32 v[10:11], v[10:11], v[212:213]
	v_lshlrev_b32_e32 v226, 16, v215
	v_and_b32_e32 v227, 0xffff0000, v215
	v_and_b32_e32 v215, 0xffff0000, v214
	v_lshlrev_b32_e32 v214, 16, v214
	v_pk_add_f32 v[8:9], v[8:9], v[226:227]
	v_pk_add_f32 v[6:7], v[6:7], v[214:215]
	v_lshlrev_b32_e32 v240, 16, v217
	v_and_b32_e32 v241, 0xffff0000, v217
	v_and_b32_e32 v217, 0xffff0000, v216
	v_lshlrev_b32_e32 v216, 16, v216
	v_pk_add_f32 v[4:5], v[4:5], v[240:241]
	v_pk_add_f32 v[2:3], v[2:3], v[216:217]
	v_cvt_pk_bf16_f32 v14, v14, v15
	v_cvt_pk_bf16_f32 v15, v16, v17
	v_cvt_pk_bf16_f32 v10, v10, v11
	v_cvt_pk_bf16_f32 v11, v12, v13
	v_cvt_pk_bf16_f32 v6, v6, v7
	v_cvt_pk_bf16_f32 v7, v8, v9
	v_cvt_pk_bf16_f32 v2, v2, v3
	v_cvt_pk_bf16_f32 v3, v4, v5
	ds_bpermute_b32 v210, v244, v14
	ds_bpermute_b32 v211, v244, v15
	ds_bpermute_b32 v212, v244, v10
	ds_bpermute_b32 v213, v244, v11
	ds_bpermute_b32 v214, v245, v14
	ds_bpermute_b32 v215, v245, v15
	ds_bpermute_b32 v216, v245, v10
	ds_bpermute_b32 v217, v245, v11
	s_waitcnt lgkmcnt(0)
	v_cndmask_b32_e64 v210, v210, v212, s[98:99]
	v_cndmask_b32_e64 v211, v211, v213, s[98:99]
	v_add_u32_e32 v212, 0x58000, v246
	global_store_dwordx2 v212, v[210:211], s[8:9]
	v_cndmask_b32_e64 v214, v214, v216, s[98:99]
	v_cndmask_b32_e64 v215, v215, v217, s[98:99]
	v_add_u32_e32 v216, 0x5c000, v246
	global_store_dwordx2 v216, v[214:215], s[8:9]
	ds_bpermute_b32 v210, v244, v6
	ds_bpermute_b32 v211, v244, v7
	ds_bpermute_b32 v212, v244, v2
	ds_bpermute_b32 v213, v244, v3
	ds_bpermute_b32 v214, v245, v6
	ds_bpermute_b32 v215, v245, v7
	ds_bpermute_b32 v216, v245, v2
	ds_bpermute_b32 v217, v245, v3
	s_waitcnt lgkmcnt(0)
	v_cndmask_b32_e64 v210, v210, v212, s[98:99]
	v_cndmask_b32_e64 v211, v211, v213, s[98:99]
	v_add_u32_e32 v212, 0x58000, v246
	global_store_dwordx2 v212, v[210:211], s[8:9] offset:256
	v_cndmask_b32_e64 v214, v214, v216, s[98:99]
	v_cndmask_b32_e64 v215, v215, v217, s[98:99]
	v_add_u32_e32 v216, 0x5c000, v246
	global_store_dwordx2 v216, v[214:215], s[8:9] offset:256
	s_and_b64 vcc, exec, s[40:41]
	s_mov_b32 s84, s65
	s_mov_b32 s56, s66
	s_cbranch_vccz .LBB0_1522
	s_waitcnt vmcnt(0)
	s_cmpk_gt_u32 s3, 0xff
	s_cbranch_scc1 .LBB0_1527
	s_barrier

; DI float bflo(unsigned u) { return __uint_as_float(u << 16); }
; DI float bfhi(unsigned u) { return __uint_as_float(u & 0xffff0000u); }
; DI void phase_final(const Params& p) {
;     const int lane = threadIdx.x & 63, gw = blockIdx.x * 8 + (threadIdx.x >> 6), nw = gridDim.x * 8;
;     const bf16_t* x2 = (const bf16_t*)(p.ws + WS_X2); const bf16_t* x1 = (const bf16_t*)(p.ws + WS_X1);
;     for (int tok = gw; tok < T_TOK; tok += nw) {
;         f32x4 v[4]; float ss = 0.f;
; #pragma unroll
;         for (int i = 0; i < 4; ++i) { const int c = 4 * lane + 256 * i;
;             if (tok < T_PR) { const u32x2 t = *(const u32x2*)(x2 + (size_t)tok * 1024 + c); v[i] = (f32x4){bflo(t.x), bfhi(t.x), bflo(t.y), bfhi(t.y)}; }
;             else { const size_t o = (size_t)(tok - T_PR) * 1024 + c; const u32x2 t = *(const u32x2*)(x1 + (size_t)tok * 1024 + c); v[i] = (f32x4){bflo(t.x), bfhi(t.x), bflo(t.y), bfhi(t.y)};
;     ...
;         for (int i = 0; i < 4; ++i) { const f32x4 ww = *(const f32x4*)(p.fnorm_w + 4 * lane + 256 * i);
.LBB0_1610:
	s_cmp_lt_i32 s80, 13
	s_cselect_b64 s[2:3], -1, 0
	s_and_b64 s[0:1], s[2:3], s[0:1]
	s_and_b64 s[0:1], s[44:45], s[0:1]
	s_and_saveexec_b64 s[2:3], s[0:1]
	s_cbranch_execz .LBB0_1629
	v_readlane_b32 s14, v238, 16
	v_readlane_b32 s15, v238, 17
	v_lshlrev_b32_e32 v2, 4, v196
	v_lshlrev_b32_e32 v3, 3, v196
	s_nop 3
	global_load_dwordx4 v[16:19], v2, s[14:15] nt
	global_load_dwordx4 v[20:23], v2, s[14:15] offset:1024 nt
	global_load_dwordx4 v[24:27], v2, s[14:15] offset:2048 nt
	global_load_dwordx4 v[28:31], v2, s[14:15] offset:3072 nt
	v_readfirstlane_b32 s4, v162
	s_add_u32 s8, s78, 0x10880000
	s_addc_u32 s9, s79, 0
	s_mov_b32 s7, 0
	s_cmp_lt_u32 s4, 0x4000
	s_cbranch_scc0 .Lfin_sample
	s_lshl_b32 s5, s4, 11
	v_add_u32_e32 v4, s5, v3
	global_load_dwordx2 v[32:33], v4, s[8:9] nt
	global_load_dwordx2 v[34:35], v4, s[8:9] offset:512 nt
	global_load_dwordx2 v[36:37], v4, s[8:9] offset:1024 nt
	global_load_dwordx2 v[38:39], v4, s[8:9] offset:1536 nt
	v_mov_b32_e32 v60, 0x358637bd
.Lfin_a:
	s_add_u32 s6, s4, s46
	s_cmp_lt_u32 s6, 0x4000
	s_cbranch_scc0 .Lfin_a_nonext
	s_lshl_b32 s5, s6, 11
	v_add_u32_e32 v5, s5, v3
	global_load_dwordx2 v[40:41], v5, s[8:9] nt
	global_load_dwordx2 v[42:43], v5, s[8:9] offset:512 nt
	global_load_dwordx2 v[44:45], v5, s[8:9] offset:1024 nt
	global_load_dwordx2 v[46:47], v5, s[8:9] offset:1536 nt
	s_cmp_eq_u32 s7, 0
	s_cbranch_scc1 .Lfin_a_w4
	s_waitcnt vmcnt(8)
	s_branch .Lfin_a_have

; DI float bflo(unsigned u) { return __uint_as_float(u << 16); }
; DI float bfhi(unsigned u) { return __uint_as_float(u & 0xffff0000u); }
; DI void phase_final(const Params& p) {
;     ...
;     for (int tok = gw; tok < T_TOK; tok += nw) {
;         f32x4 v[4]; float ss = 0.f;
; #pragma unroll
;         for (int i = 0; i < 4; ++i) { const int c = 4 * lane + 256 * i;
;             if (tok < T_PR) { const u32x2 t = *(const u32x2*)(x2 + (size_t)tok * 1024 + c); v[i] = (f32x4){bflo(t.x), bfhi(t.x), bflo(t.y), bfhi(t.y)}; }
.Lfin_b:
	s_add_u32 s6, s4, s46
	s_cmp_lt_u32 s6, 0x4000
	s_cbranch_scc0 .Lfin_b_nonext
	s_lshl_b32 s5, s6, 11
	v_add_u32_e32 v5, s5, v3
	global_load_dwordx2 v[32:33], v5, s[8:9] nt
	global_load_dwordx2 v[34:35], v5, s[8:9] offset:512 nt
	global_load_dwordx2 v[36:37], v5, s[8:9] offset:1024 nt
	global_load_dwordx2 v[38:39], v5, s[8:9] offset:1536 nt
	s_cmp_eq_u32 s7, 0
	s_cbranch_scc1 .Lfin_b_w4
	s_waitcnt vmcnt(8)
	s_branch .Lfin_b_have

; DI float bflo(unsigned u) { return __uint_as_float(u << 16); }
; DI float bfhi(unsigned u) { return __uint_as_float(u & 0xffff0000u); }
; DI void phase_final(const Params& p) {
;     ...
;             else { const size_t o = (size_t)(tok - T_PR) * 1024 + c; const u32x2 t = *(const u32x2*)(x1 + (size_t)tok * 1024 + c); v[i] = (f32x4){bflo(t.x), bfhi(t.x), bflo(t.y), bfhi(t.y)};
; #pragma unroll
;                 for (int s = 0; s < 8; ++s) v[i] += *(const f32x4*)((const float*)(p.ws + WS_PART2) + (size_t)s * 1048576 + o); }
.Lfin_sample:
	s_cmp_lt_u32 s4, 0x4400
	s_cbranch_scc0 .Lfin_done
	v_mov_b32_e32 v60, 0x358637bd
	s_add_u32 s8, s78, 0xc480000
	s_addc_u32 s9, s79, 0
	s_lshl_b32 s5, s4, 11
	v_add_u32_e32 v4, s5, v3
	global_load_dwordx2 v[32:33], v4, s[8:9] nt
	global_load_dwordx2 v[34:35], v4, s[8:9] offset:512 nt
	global_load_dwordx2 v[36:37], v4, s[8:9] offset:1024 nt
	global_load_dwordx2 v[38:39], v4, s[8:9] offset:1536 nt
	s_sub_u32 s5, s4, 0x4000
	s_lshl_b32 s5, s5, 12
	s_add_u32 s12, s78, 0x14c80000
	s_addc_u32 s13, s79, 0
	s_add_u32 s12, s12, s5
	s_addc_u32 s13, s13, 0
	global_load_dwordx4 v[80:83], v2, s[12:13] nt
	global_load_dwordx4 v[84:87], v2, s[12:13] offset:1024 nt
	global_load_dwordx4 v[88:91], v2, s[12:13] offset:2048 nt
	global_load_dwordx4 v[92:95], v2, s[12:13] offset:3072 nt
	s_add_u32 s12, s12, 0x400000
	s_addc_u32 s13, s13, 0
	global_load_dwordx4 v[96:99], v2, s[12:13] nt
	global_load_dwordx4 v[100:103], v2, s[12:13] offset:1024 nt
	global_load_dwordx4 v[104:107], v2, s[12:13] offset:2048 nt
	global_load_dwordx4 v[108:111], v2, s[12:13] offset:3072 nt
	s_add_u32 s12, s12, 0x400000
	s_addc_u32 s13, s13, 0
	global_load_dwordx4 v[112:115], v2, s[12:13] nt
	global_load_dwordx4 v[116:119], v2, s[12:13] offset:1024 nt
	global_load_dwordx4 v[120:123], v2, s[12:13] offset:2048 nt
	global_load_dwordx4 v[124:127], v2, s[12:13] offset:3072 nt
	s_add_u32 s12, s12, 0x400000
	s_addc_u32 s13, s13, 0
	global_load_dwordx4 v[128:131], v2, s[12:13] nt
	global_load_dwordx4 v[132:135], v2, s[12:13] offset:1024 nt
	global_load_dwordx4 v[136:139], v2, s[12:13] offset:2048 nt
	global_load_dwordx4 v[140:143], v2, s[12:13] offset:3072 nt
	s_add_u32 s12, s12, 0x400000
	s_addc_u32 s13, s13, 0
	global_load_dwordx4 v[144:147], v2, s[12:13] nt
	global_load_dwordx4 v[148:151], v2, s[12:13] offset:1024 nt
	global_load_dwordx4 v[152:155], v2, s[12:13] offset:2048 nt
	global_load_dwordx4 v[156:159], v2, s[12:13] offset:3072 nt
	s_add_u32 s12, s12, 0x400000
	s_addc_u32 s13, s13, 0
	global_load_dwordx4 v[160:163], v2, s[12:13] nt
	global_load_dwordx4 v[164:167], v2, s[12:13] offset:1024 nt
	global_load_dwordx4 v[168:171], v2, s[12:13] offset:2048 nt
	global_load_dwordx4 v[172:175], v2, s[12:13] offset:3072 nt
	s_add_u32 s12, s12, 0x400000
	s_addc_u32 s13, s13, 0
	global_load_dwordx4 v[176:179], v2, s[12:13] nt
	global_load_dwordx4 v[180:183], v2, s[12:13] offset:1024 nt
	global_load_dwordx4 v[184:187], v2, s[12:13] offset:2048 nt
	global_load_dwordx4 v[188:191], v2, s[12:13] offset:3072 nt
	s_add_u32 s12, s12, 0x400000
	s_addc_u32 s13, s13, 0
	global_load_dwordx4 v[192:195], v2, s[12:13] nt
	global_load_dwordx4 v[196:199], v2, s[12:13] offset:1024 nt
	global_load_dwordx4 v[200:203], v2, s[12:13] offset:2048 nt
	global_load_dwordx4 v[204:207], v2, s[12:13] offset:3072 nt
	s_waitcnt vmcnt(0)
; DI float bflo(unsigned u) { return __uint_as_float(u << 16); }
; DI float bfhi(unsigned u) { return __uint_as_float(u & 0xffff0000u); }
; DI void phase_final(const Params& p) {
;     ...
;             else { const size_t o = (size_t)(tok - T_PR) * 1024 + c; const u32x2 t = *(const u32x2*)(x1 + (size_t)tok * 1024 + c); v[i] = (f32x4){bflo(t.x), bfhi(t.x), bflo(t.y), bfhi(t.y)};
; #pragma unroll
;                 for (int s = 0; s < 8; ++s) v[i] += *(const f32x4*)((const float*)(p.ws + WS_PART2) + (size_t)s * 1048576 + o); }
;             ss += v[i].x * v[i].x + v[i].y * v[i].y + v[i].z * v[i].z + v[i].w * v[i].w; }
;         ss = wave_sum(ss);
;         const float rstd = rsqrtf(ss * (1.f / 1024.f) + 1e-6f);
; #pragma unroll
;         for (int i = 0; i < 4; ++i) { const f32x4 ww = *(const f32x4*)(p.fnorm_w + 4 * lane + 256 * i);
;             *(f32x4*)(p.out + O_Y + (size_t)tok * 1024 + 4 * lane + 256 * i) = (f32x4){v[i].x * rstd * ww.x, v[i].y * rstd * ww.y, v[i].z * rstd * ww.z, v[i].w * rstd * ww.w}; }
	v_lshlrev_b32_e32 v64, 16, v32
	v_and_b32_e32 v65, 0xffff0000, v32
	v_lshlrev_b32_e32 v66, 16, v33
	v_and_b32_e32 v67, 0xffff0000, v33
	v_lshlrev_b32_e32 v68, 16, v34
	v_and_b32_e32 v69, 0xffff0000, v34
	v_lshlrev_b32_e32 v70, 16, v35
	v_and_b32_e32 v71, 0xffff0000, v35
	v_lshlrev_b32_e32 v72, 16, v36
	v_and_b32_e32 v73, 0xffff0000, v36
	v_lshlrev_b32_e32 v74, 16, v37
	v_and_b32_e32 v75, 0xffff0000, v37
	v_lshlrev_b32_e32 v76, 16, v38
	v_and_b32_e32 v77, 0xffff0000, v38
	v_lshlrev_b32_e32 v78, 16, v39
	v_and_b32_e32 v79, 0xffff0000, v39
	v_add_f32_e32 v64, v64, v80
	v_add_f32_e32 v65, v65, v81
	v_add_f32_e32 v66, v66, v82
	v_add_f32_e32 v67, v67, v83
	v_add_f32_e32 v68, v68, v84
	v_add_f32_e32 v69, v69, v85
	v_add_f32_e32 v70, v70, v86
	v_add_f32_e32 v71, v71, v87
	v_add_f32_e32 v72, v72, v88
	v_add_f32_e32 v73, v73, v89
	v_add_f32_e32 v74, v74, v90
	v_add_f32_e32 v75, v75, v91
	v_add_f32_e32 v76, v76, v92
	v_add_f32_e32 v77, v77, v93
	v_add_f32_e32 v78, v78, v94
	v_add_f32_e32 v79, v79, v95
	v_add_f32_e32 v64, v64, v96
	v_add_f32_e32 v65, v65, v97
	v_add_f32_e32 v66, v66, v98
	v_add_f32_e32 v67, v67, v99
	v_add_f32_e32 v68, v68, v100
	v_add_f32_e32 v69, v69, v101
	v_add_f32_e32 v70, v70, v102
	v_add_f32_e32 v71, v71, v103
	v_add_f32_e32 v72, v72, v104
	v_add_f32_e32 v73, v73, v105
	v_add_f32_e32 v74, v74, v106
	v_add_f32_e32 v75, v75, v107
	v_add_f32_e32 v76, v76, v108
	v_add_f32_e32 v77, v77, v109
	v_add_f32_e32 v78, v78, v110
	v_add_f32_e32 v79, v79, v111
	v_add_f32_e32 v64, v64, v112
	v_add_f32_e32 v65, v65, v113
	v_add_f32_e32 v66, v66, v114
	v_add_f32_e32 v67, v67, v115
	v_add_f32_e32 v68, v68, v116
	v_add_f32_e32 v69, v69, v117
	v_add_f32_e32 v70, v70, v118
	v_add_f32_e32 v71, v71, v119
	v_add_f32_e32 v72, v72, v120
	v_add_f32_e32 v73, v73, v121
	v_add_f32_e32 v74, v74, v122
	v_add_f32_e32 v75, v75, v123
	v_add_f32_e32 v76, v76, v124
	v_add_f32_e32 v77, v77, v125
	v_add_f32_e32 v78, v78, v126
	v_add_f32_e32 v79, v79, v127
	v_add_f32_e32 v64, v64, v128
	v_add_f32_e32 v65, v65, v129
	v_add_f32_e32 v66, v66, v130
	v_add_f32_e32 v67, v67, v131
	v_add_f32_e32 v68, v68, v132
	v_add_f32_e32 v69, v69, v133
	v_add_f32_e32 v70, v70, v134
	v_add_f32_e32 v71, v71, v135
	v_add_f32_e32 v72, v72, v136
	v_add_f32_e32 v73, v73, v137
	v_add_f32_e32 v74, v74, v138
	v_add_f32_e32 v75, v75, v139
	v_add_f32_e32 v76, v76, v140
	v_add_f32_e32 v77, v77, v141
	v_add_f32_e32 v78, v78, v142
	v_add_f32_e32 v79, v79, v143
	v_add_f32_e32 v64, v64, v144
	v_add_f32_e32 v65, v65, v145
	v_add_f32_e32 v66, v66, v146
	v_add_f32_e32 v67, v67, v147
	v_add_f32_e32 v68, v68, v148
	v_add_f32_e32 v69, v69, v149
	v_add_f32_e32 v70, v70, v150
	v_add_f32_e32 v71, v71, v151
	v_add_f32_e32 v72, v72, v152
	v_add_f32_e32 v73, v73, v153
	v_add_f32_e32 v74, v74, v154
	v_add_f32_e32 v75, v75, v155
	v_add_f32_e32 v76, v76, v156
	v_add_f32_e32 v77, v77, v157
	v_add_f32_e32 v78, v78, v158
	v_add_f32_e32 v79, v79, v159
	v_add_f32_e32 v64, v64, v160
	v_add_f32_e32 v65, v65, v161
	v_add_f32_e32 v66, v66, v162
	v_add_f32_e32 v67, v67, v163
	v_add_f32_e32 v68, v68, v164
	v_add_f32_e32 v69, v69, v165
	v_add_f32_e32 v70, v70, v166
	v_add_f32_e32 v71, v71, v167
	v_add_f32_e32 v72, v72, v168
	v_add_f32_e32 v73, v73, v169
	v_add_f32_e32 v74, v74, v170
	v_add_f32_e32 v75, v75, v171
	v_add_f32_e32 v76, v76, v172
	v_add_f32_e32 v77, v77, v173
	v_add_f32_e32 v78, v78, v174
	v_add_f32_e32 v79, v79, v175
	v_add_f32_e32 v64, v64, v176
	v_add_f32_e32 v65, v65, v177
	v_add_f32_e32 v66, v66, v178
	v_add_f32_e32 v67, v67, v179
	v_add_f32_e32 v68, v68, v180
	v_add_f32_e32 v69, v69, v181
	v_add_f32_e32 v70, v70, v182
	v_add_f32_e32 v71, v71, v183
	v_add_f32_e32 v72, v72, v184
	v_add_f32_e32 v73, v73, v185
	v_add_f32_e32 v74, v74, v186
	v_add_f32_e32 v75, v75, v187
	v_add_f32_e32 v76, v76, v188
	v_add_f32_e32 v77, v77, v189
	v_add_f32_e32 v78, v78, v190
	v_add_f32_e32 v79, v79, v191
	v_add_f32_e32 v64, v64, v192
	v_add_f32_e32 v65, v65, v193
	v_add_f32_e32 v66, v66, v194
	v_add_f32_e32 v67, v67, v195
	v_add_f32_e32 v68, v68, v196
	v_add_f32_e32 v69, v69, v197
	v_add_f32_e32 v70, v70, v198
	v_add_f32_e32 v71, v71, v199
	v_add_f32_e32 v72, v72, v200
	v_add_f32_e32 v73, v73, v201
	v_add_f32_e32 v74, v74, v202
	v_add_f32_e32 v75, v75, v203
	v_add_f32_e32 v76, v76, v204
	v_add_f32_e32 v77, v77, v205
	v_add_f32_e32 v78, v78, v206
	v_add_f32_e32 v79, v79, v207
	v_mul_f32_e32 v48, v64, v64
	v_fmac_f32_e32 v48, v65, v65
	v_fmac_f32_e32 v48, v66, v66
	v_fmac_f32_e32 v48, v67, v67
	v_mul_f32_e32 v49, v68, v68
	v_fmac_f32_e32 v49, v69, v69
	v_fmac_f32_e32 v49, v70, v70
	v_fmac_f32_e32 v49, v71, v71
	v_mul_f32_e32 v50, v72, v72
	v_fmac_f32_e32 v50, v73, v73
	v_fmac_f32_e32 v50, v74, v74
	v_fmac_f32_e32 v50, v75, v75
	v_mul_f32_e32 v51, v76, v76
	v_fmac_f32_e32 v51, v77, v77
	v_fmac_f32_e32 v51, v78, v78
	v_fmac_f32_e32 v51, v79, v79
	v_add_f32_e32 v48, v48, v49
	v_add_f32_e32 v50, v50, v51
	v_add_f32_e32 v48, v48, v50
	s_nop 1
	v_add_f32_dpp v48, v48, v48 quad_perm:[1,0,3,2] row_mask:0xf bank_mask:0xf bound_ctrl:1
	s_nop 1
	v_add_f32_dpp v48, v48, v48 quad_perm:[2,3,0,1] row_mask:0xf bank_mask:0xf bound_ctrl:1
	s_nop 1
	v_add_f32_dpp v48, v48, v48 row_ror:4 row_mask:0xf bank_mask:0xf bound_ctrl:1
	s_nop 1
	v_add_f32_dpp v48, v48, v48 row_ror:8 row_mask:0xf bank_mask:0xf bound_ctrl:1
	s_nop 1
	v_readlane_b32 s16, v48, 0
	v_readlane_b32 s17, v48, 16
	v_readlane_b32 s18, v48, 32
	v_readlane_b32 s19, v48, 48
	s_nop 1
	v_mov_b32_e32 v52, s16
	v_add_f32_e32 v52, s17, v52
	v_add_f32_e32 v52, s18, v52
	v_add_f32_e32 v52, s19, v52
	v_fmamk_f32 v52, v52, 0x3a800000, v60
	v_rsq_f32_e32 v52, v52
	s_mov_b32 s11, 0
	s_lshl_b32 s10, s4, 12
	s_add_u32 s10, s76, s10
	s_addc_u32 s11, s77, 0
	v_mul_f32_e32 v64, v64, v52
	v_mul_f32_e32 v65, v65, v52
	v_mul_f32_e32 v66, v66, v52
	v_mul_f32_e32 v67, v67, v52
	v_mul_f32_e32 v64, v64, v16
	v_mul_f32_e32 v65, v65, v17
	v_mul_f32_e32 v66, v66, v18
	v_mul_f32_e32 v67, v67, v19
	global_store_dwordx4 v2, v[64:67], s[10:11]
	v_mul_f32_e32 v68, v68, v52
	v_mul_f32_e32 v69, v69, v52
	v_mul_f32_e32 v70, v70, v52
	v_mul_f32_e32 v71, v71, v52
	v_mul_f32_e32 v68, v68, v20
	v_mul_f32_e32 v69, v69, v21
	v_mul_f32_e32 v70, v70, v22
	v_mul_f32_e32 v71, v71, v23
	global_store_dwordx4 v2, v[68:71], s[10:11] offset:1024
	v_mul_f32_e32 v72, v72, v52
	v_mul_f32_e32 v73, v73, v52
	v_mul_f32_e32 v74, v74, v52
	v_mul_f32_e32 v75, v75, v52
	v_mul_f32_e32 v72, v72, v24
	v_mul_f32_e32 v73, v73, v25
	v_mul_f32_e32 v74, v74, v26
	v_mul_f32_e32 v75, v75, v27
	global_store_dwordx4 v2, v[72:75], s[10:11] offset:2048
	v_mul_f32_e32 v76, v76, v52
	v_mul_f32_e32 v77, v77, v52
	v_mul_f32_e32 v78, v78, v52
	v_mul_f32_e32 v79, v79, v52
	v_mul_f32_e32 v76, v76, v28
	v_mul_f32_e32 v77, v77, v29
	v_mul_f32_e32 v78, v78, v30
	v_mul_f32_e32 v79, v79, v31
	global_store_dwordx4 v2, v[76:79], s[10:11] offset:3072
